# v41 plus: compiled lgkmcnt(0) waits right after each re-laid store in P4,P7,P9 relaxed to lgkmcnt(4) (only the 4 just-issued lane permutes are younger)
# speedup vs baseline: 1.0140x; 1.0006x over previous
; __device__ __forceinline__ unsigned cvt_pk_bf16(float lo, float hi) { unsigned r; asm volatile("v_cvt_pk_bf16_f32 %0, %1, %2" : "=v"(r) : "v"(lo), "v"(hi)); return r; }
;     __device__ __forceinline__ void operator()(const f32x4 (&acc)[2][2][4][2], const Unit& u, int wr, int wc, int fr, int fq) const {
;     ...
;                 for (int bj = 0; bj < 2; ++bj) { const size_t off = (size_t)(row0 + ai * HALF + m * 16) * 1024 + col0 + bj * HALF;
;                     if (BASE_BF16) bw[m][bj] = *(const u32x4*)((const bf16_t*)base + off);
;                     else { bf[m][bj][0] = *(const f32x4*)((const float*)base + off); bf[m][bj][1] = *(const f32x4*)((const float*)base + off + 4); } }
; #pragma unroll
;             for (int m = 0; m < 4; ++m) {
;                 const int row = row0 + ai * HALF + m * 16; const size_t off = (size_t)row * 1024 + col0;
;                 float ss = 0.f;
; #pragma unroll
;                 for (int bj = 0; bj < 2; ++bj) {
;                     f32x4 b0, b1;
;                     if (BASE_BF16) { const u32x4 w = bw[m][bj];
;                         b0 = (f32x4){__builtin_bit_cast(float, w.x << 16), __builtin_bit_cast(float, w.x & 0xffff0000u), __builtin_bit_cast(float, w.y << 16), __builtin_bit_cast(float, w.y & 0xffff0000u)};
;                         b1 = (f32x4){__builtin_bit_cast(float, w.z << 16), __builtin_bit_cast(float, w.z & 0xffff0000u), __builtin_bit_cast(float, w.w << 16), __builtin_bit_cast(float, w.w & 0xffff0000u)}; }
;                     else { b0 = bf[m][bj][0]; b1 = bf[m][bj][1]; }
;                     const f32x4 v0 = acc[ai][bj][m][0] + b0, v1 = acc[ai][bj][m][1] + b1;
;                     ss += (v0[0] * v0[0] + v0[1] * v0[1]) + (v0[2] * v0[2] + v0[3] * v0[3]) + (v1[0] * v1[0] + v1[1] * v1[1]) + (v1[2] * v1[2] + v1[3] * v1[3]);
;                     if (OUT_BF16) { u32x4 w; w.x = cvt_pk_bf16(v0[0], v0[1]); w.y = cvt_pk_bf16(v0[2], v0[3]); w.z = cvt_pk_bf16(v1[0], v1[1]); w.w = cvt_pk_bf16(v1[2], v1[3]);
;                         *(u32x4*)((bf16_t*)out + off + bj * HALF) = w; }
;                     else { *(f32x4*)((float*)out + off + bj * HALF) = v0; *(f32x4*)((float*)out + off + bj * HALF + 4) = v1; }
;                 }
;                 ss += __shfl_xor(ss, 16); ss += __shfl_xor(ss, 32);
;                 if (fq == 0) sspart[(size_t)row * 16 + u.pn * 4 + wc] = ss;
.LBB0_919:
	v_lshl_or_b32 v168, s8, 8, v190
	v_lshl_add_u32 v172, s30, 8, v188
	v_ashrrev_i32_e32 v169, 31, v168
	v_lshlrev_b64 v[202:203], 1, v[168:169]
	v_ashrrev_i32_e32 v173, 31, v172
	v_lshl_add_u64 v[170:171], s[12:13], 0, v[202:203]
	v_lshlrev_b64 v[204:205], 11, v[172:173]
	v_lshl_add_u64 v[128:129], v[170:171], 0, v[204:205]
	global_load_dwordx4 v[194:197], v[128:129], off
	global_load_dwordx4 v[198:201], v[128:129], off offset:256
	v_or_b32_e32 v182, 16, v172
	v_or_b32_e32 v178, 32, v172
	v_or_b32_e32 v174, 48, v172
	v_ashrrev_i32_e32 v183, 31, v182
	v_ashrrev_i32_e32 v179, 31, v178
	v_ashrrev_i32_e32 v175, 31, v174
	v_lshlrev_b64 v[184:185], 11, v[182:183]
	v_lshlrev_b64 v[180:181], 11, v[178:179]
	v_lshlrev_b64 v[176:177], 11, v[174:175]
	v_lshl_add_u64 v[128:129], v[170:171], 0, v[184:185]
	v_lshl_add_u64 v[130:131], v[170:171], 0, v[180:181]
	v_lshl_add_u64 v[206:207], v[170:171], 0, v[176:177]
	global_load_dwordx4 v[148:151], v[128:129], off
	global_load_dwordx4 v[144:147], v[128:129], off offset:256
	global_load_dwordx4 v[140:143], v[130:131], off
	global_load_dwordx4 v[136:139], v[130:131], off offset:256
	global_load_dwordx4 v[132:135], v[206:207], off
	s_nop 0
	global_load_dwordx4 v[128:131], v[206:207], off offset:256
	s_lshl_b32 s30, s8, 2
	s_ashr_i32 s31, s30, 31
	s_waitcnt vmcnt(0)
	v_lshlrev_b32_e32 v206, 16, v194
	v_and_b32_e32 v207, 0xffff0000, v194
	v_lshlrev_b32_e32 v194, 16, v195
	v_and_b32_e32 v195, 0xffff0000, v195
	v_lshlrev_b32_e32 v208, 16, v196
	v_and_b32_e32 v209, 0xffff0000, v196
	v_lshlrev_b32_e32 v196, 16, v197
	v_and_b32_e32 v197, 0xffff0000, v197
	v_lshlrev_b32_e32 v210, 16, v198
	v_and_b32_e32 v211, 0xffff0000, v198
	v_lshlrev_b32_e32 v198, 16, v199
	v_and_b32_e32 v199, 0xffff0000, v199
	v_lshlrev_b32_e32 v214, 16, v200
	v_and_b32_e32 v215, 0xffff0000, v200
	v_lshlrev_b32_e32 v200, 16, v201
	v_and_b32_e32 v201, 0xffff0000, v201
	v_pk_add_f32 v[126:127], v[126:127], v[194:195]
	v_pk_add_f32 v[124:125], v[124:125], v[206:207]
	v_pk_add_f32 v[122:123], v[122:123], v[196:197]
	v_pk_add_f32 v[120:121], v[120:121], v[208:209]
	v_pk_add_f32 v[118:119], v[118:119], v[198:199]
	v_pk_add_f32 v[116:117], v[116:117], v[210:211]
	v_pk_add_f32 v[194:195], v[114:115], v[200:201]
	v_pk_add_f32 v[196:197], v[112:113], v[214:215]
	v_mul_f32_e32 v198, v125, v125
	v_mul_f32_e32 v199, v127, v127
	v_mul_f32_e32 v200, v121, v121
	v_mul_f32_e32 v201, v123, v123
	v_cvt_pk_bf16_f32 v112, v124, v125
	v_cvt_pk_bf16_f32 v113, v126, v127
	v_cvt_pk_bf16_f32 v114, v120, v121
	v_cvt_pk_bf16_f32 v115, v122, v123
	v_mul_f32_e32 v121, v117, v117
	v_mul_f32_e32 v123, v119, v119
	v_mul_f32_e32 v125, v197, v197
	v_fmac_f32_e32 v198, v124, v124
	v_fmac_f32_e32 v199, v126, v126
	v_fmac_f32_e32 v121, v116, v116
	v_fmac_f32_e32 v123, v118, v118
	v_mul_f32_e32 v127, v195, v195
	v_fmac_f32_e32 v200, v120, v120
	v_fmac_f32_e32 v125, v196, v196
	v_add_f32_e32 v120, v198, v199
	v_add_f32_e32 v121, v121, v123
	v_fmac_f32_e32 v201, v122, v122
	v_fmac_f32_e32 v127, v194, v194
	v_add_f32_e32 v120, v200, v120
	v_add_f32_e32 v121, v125, v121
	v_add_f32_e32 v120, v201, v120
	v_add_f32_e32 v121, v127, v121
	v_add_f32_e32 v122, v120, v121
	ds_bpermute_b32 v123, v186, v122
	v_lshl_add_u64 v[120:121], s[12:13], 0, v[204:205]
	v_lshl_add_u64 v[120:121], v[120:121], 0, v[202:203]
	ds_bpermute_b32 v240, v253, v112
	ds_bpermute_b32 v241, v253, v113
	ds_bpermute_b32 v242, v253, v114
	ds_bpermute_b32 v243, v253, v115
	v_lshl_add_u64 v[236:237], v[120:121], 0, v[250:251]
	s_waitcnt lgkmcnt(4)
	s_nop 0
	v_add_f32_e32 v112, v122, v123
	ds_bpermute_b32 v113, v187, v112
	v_cvt_pk_bf16_f32 v114, v116, v117
	v_cvt_pk_bf16_f32 v115, v118, v119
	v_cvt_pk_bf16_f32 v116, v196, v197
	v_cvt_pk_bf16_f32 v117, v194, v195
	ds_bpermute_b32 v244, v253, v114
	ds_bpermute_b32 v245, v253, v115
	ds_bpermute_b32 v246, v253, v116
	ds_bpermute_b32 v247, v253, v117
	v_lshl_add_u64 v[238:239], v[120:121], 0, v[250:251]
	s_waitcnt lgkmcnt(4)
	global_store_dwordx4 v[236:237], v[240:243], off
	s_and_saveexec_b64 s[34:35], s[4:5]
	s_cbranch_execz .LBB0_921
	v_lshlrev_b64 v[114:115], 6, v[172:173]
	v_lshl_add_u64 v[114:115], s[14:15], 0, v[114:115]
	v_lshl_add_u64 v[114:115], s[30:31], 2, v[114:115]
	s_lshl_b32 s8, s46, 2
	v_lshl_add_u64 v[114:115], v[114:115], 0, s[8:9]
	s_waitcnt lgkmcnt(4)
	v_add_f32_e32 v112, v112, v113
	global_store_dword v[114:115], v112, off
; __device__ __forceinline__ unsigned cvt_pk_bf16(float lo, float hi) { unsigned r; asm volatile("v_cvt_pk_bf16_f32 %0, %1, %2" : "=v"(r) : "v"(lo), "v"(hi)); return r; }
;     __device__ __forceinline__ void operator()(const f32x4 (&acc)[2][2][4][2], const Unit& u, int wr, int wc, int fr, int fq) const {
;     ...
;             for (int m = 0; m < 4; ++m) {
;                 const int row = row0 + ai * HALF + m * 16; const size_t off = (size_t)row * 1024 + col0;
;                 float ss = 0.f;
; #pragma unroll
;                 for (int bj = 0; bj < 2; ++bj) {
;                     f32x4 b0, b1;
;                     if (BASE_BF16) { const u32x4 w = bw[m][bj];
;                         b0 = (f32x4){__builtin_bit_cast(float, w.x << 16), __builtin_bit_cast(float, w.x & 0xffff0000u), __builtin_bit_cast(float, w.y << 16), __builtin_bit_cast(float, w.y & 0xffff0000u)};
;                         b1 = (f32x4){__builtin_bit_cast(float, w.z << 16), __builtin_bit_cast(float, w.z & 0xffff0000u), __builtin_bit_cast(float, w.w << 16), __builtin_bit_cast(float, w.w & 0xffff0000u)}; }
;                     else { b0 = bf[m][bj][0]; b1 = bf[m][bj][1]; }
;                     const f32x4 v0 = acc[ai][bj][m][0] + b0, v1 = acc[ai][bj][m][1] + b1;
;                     ss += (v0[0] * v0[0] + v0[1] * v0[1]) + (v0[2] * v0[2] + v0[3] * v0[3]) + (v1[0] * v1[0] + v1[1] * v1[1]) + (v1[2] * v1[2] + v1[3] * v1[3]);
;                     if (OUT_BF16) { u32x4 w; w.x = cvt_pk_bf16(v0[0], v0[1]); w.y = cvt_pk_bf16(v0[2], v0[3]); w.z = cvt_pk_bf16(v1[0], v1[1]); w.w = cvt_pk_bf16(v1[2], v1[3]);
;                         *(u32x4*)((bf16_t*)out + off + bj * HALF) = w; }
;                     else { *(f32x4*)((float*)out + off + bj * HALF) = v0; *(f32x4*)((float*)out + off + bj * HALF + 4) = v1; }
;                 }
;                 ss += __shfl_xor(ss, 16); ss += __shfl_xor(ss, 32);
;                 if (fq == 0) sspart[(size_t)row * 16 + u.pn * 4 + wc] = ss;
.LBB0_921:
	s_or_b64 exec, exec, s[34:35]
	v_lshlrev_b32_e32 v112, 16, v148
	s_waitcnt lgkmcnt(0)
	v_and_b32_e32 v113, 0xffff0000, v148
	v_lshlrev_b32_e32 v114, 16, v149
	v_and_b32_e32 v115, 0xffff0000, v149
	v_lshlrev_b32_e32 v116, 16, v150
	v_and_b32_e32 v117, 0xffff0000, v150
	v_lshlrev_b32_e32 v118, 16, v151
	v_and_b32_e32 v119, 0xffff0000, v151
	v_pk_add_f32 v[110:111], v[110:111], v[114:115]
	v_pk_add_f32 v[108:109], v[108:109], v[112:113]
	v_pk_add_f32 v[112:113], v[106:107], v[118:119]
	v_pk_add_f32 v[106:107], v[104:105], v[116:117]
	v_mul_f32_e32 v104, v109, v109
	v_mul_f32_e32 v105, v111, v111
	v_fmac_f32_e32 v104, v108, v108
	v_fmac_f32_e32 v105, v110, v110
	v_add_f32_e32 v104, v104, v105
	v_mul_f32_e32 v105, v107, v107
	v_fmac_f32_e32 v105, v106, v106
	v_add_f32_e32 v104, v105, v104
	v_mul_f32_e32 v105, v113, v113
	v_fmac_f32_e32 v105, v112, v112
	v_add_f32_e32 v116, v105, v104
	v_cvt_pk_bf16_f32 v104, v108, v109
	v_cvt_pk_bf16_f32 v105, v110, v111
	v_lshlrev_b32_e32 v108, 16, v144
	v_and_b32_e32 v109, 0xffff0000, v144
	v_lshlrev_b32_e32 v110, 16, v145
	v_and_b32_e32 v111, 0xffff0000, v145
	v_cvt_pk_bf16_f32 v106, v106, v107
	v_cvt_pk_bf16_f32 v107, v112, v113
	v_lshlrev_b32_e32 v112, 16, v146
	v_and_b32_e32 v113, 0xffff0000, v146
	v_pk_add_f32 v[102:103], v[102:103], v[110:111]
	v_pk_add_f32 v[100:101], v[100:101], v[108:109]
	v_pk_add_f32 v[110:111], v[96:97], v[112:113]
	v_mul_f32_e32 v96, v101, v101
	v_mul_f32_e32 v97, v103, v103
	v_fmac_f32_e32 v96, v100, v100
	v_fmac_f32_e32 v97, v102, v102
	v_lshlrev_b32_e32 v114, 16, v147
	v_and_b32_e32 v115, 0xffff0000, v147
	v_add_f32_e32 v96, v96, v97
	v_mul_f32_e32 v97, v111, v111
	v_pk_add_f32 v[108:109], v[98:99], v[114:115]
	v_fmac_f32_e32 v97, v110, v110
	v_add_f32_e32 v96, v97, v96
	v_mul_f32_e32 v97, v109, v109
	v_fmac_f32_e32 v97, v108, v108
	v_add_f32_e32 v96, v97, v96
	v_add_f32_e32 v99, v116, v96
	ds_bpermute_b32 v114, v186, v99
	v_lshl_add_u64 v[96:97], s[12:13], 0, v[184:185]
	v_lshl_add_u64 v[112:113], v[168:169], 1, v[96:97]
	ds_bpermute_b32 v240, v253, v104
	ds_bpermute_b32 v241, v253, v105
	ds_bpermute_b32 v242, v253, v106
	ds_bpermute_b32 v243, v253, v107
	v_lshl_add_u64 v[236:237], v[112:113], 0, v[250:251]
	s_waitcnt lgkmcnt(4)
	global_store_dwordx4 v[238:239], v[244:247], off offset:256
	v_cvt_pk_bf16_f32 v98, v100, v101
	s_waitcnt lgkmcnt(4)
	v_add_f32_e32 v96, v99, v114
	ds_bpermute_b32 v97, v187, v96
	v_cvt_pk_bf16_f32 v99, v102, v103
	v_cvt_pk_bf16_f32 v100, v110, v111
	v_cvt_pk_bf16_f32 v101, v108, v109
	ds_bpermute_b32 v244, v253, v98
	ds_bpermute_b32 v245, v253, v99
	ds_bpermute_b32 v246, v253, v100
	ds_bpermute_b32 v247, v253, v101
	v_lshl_add_u64 v[238:239], v[112:113], 0, v[250:251]
	s_waitcnt lgkmcnt(4)
	global_store_dwordx4 v[236:237], v[240:243], off
	s_and_saveexec_b64 s[34:35], s[4:5]
	s_cbranch_execz .LBB0_923
	v_lshlrev_b64 v[98:99], 6, v[182:183]
	v_lshl_add_u64 v[98:99], s[14:15], 0, v[98:99]
	v_lshl_add_u64 v[98:99], s[30:31], 2, v[98:99]
	s_lshl_b32 s8, s46, 2
	v_lshl_add_u64 v[98:99], v[98:99], 0, s[8:9]
	s_waitcnt lgkmcnt(4)
	v_add_f32_e32 v96, v96, v97
	global_store_dword v[98:99], v96, off
.LBB0_923:
	s_or_b64 exec, exec, s[34:35]
	v_lshlrev_b32_e32 v96, 16, v140
	s_waitcnt lgkmcnt(0)
	v_and_b32_e32 v97, 0xffff0000, v140
	v_lshlrev_b32_e32 v98, 16, v141
	v_and_b32_e32 v99, 0xffff0000, v141
	v_lshlrev_b32_e32 v100, 16, v142
	v_and_b32_e32 v101, 0xffff0000, v142
	v_lshlrev_b32_e32 v102, 16, v143
	v_and_b32_e32 v103, 0xffff0000, v143
	v_pk_add_f32 v[94:95], v[94:95], v[98:99]
	v_pk_add_f32 v[92:93], v[92:93], v[96:97]
	v_pk_add_f32 v[96:97], v[90:91], v[102:103]
	v_pk_add_f32 v[90:91], v[88:89], v[100:101]
	v_mul_f32_e32 v88, v93, v93
	v_mul_f32_e32 v89, v95, v95
	v_fmac_f32_e32 v88, v92, v92
	v_fmac_f32_e32 v89, v94, v94
	v_add_f32_e32 v88, v88, v89
	v_mul_f32_e32 v89, v91, v91
	v_fmac_f32_e32 v89, v90, v90
	v_add_f32_e32 v88, v89, v88
	v_mul_f32_e32 v89, v97, v97
	v_fmac_f32_e32 v89, v96, v96
	v_add_f32_e32 v100, v89, v88
	v_cvt_pk_bf16_f32 v88, v92, v93
	v_cvt_pk_bf16_f32 v89, v94, v95
	v_lshlrev_b32_e32 v92, 16, v136
	v_and_b32_e32 v93, 0xffff0000, v136
	v_lshlrev_b32_e32 v94, 16, v137
	v_and_b32_e32 v95, 0xffff0000, v137
	v_cvt_pk_bf16_f32 v90, v90, v91
	v_cvt_pk_bf16_f32 v91, v96, v97
	v_lshlrev_b32_e32 v96, 16, v138
	v_and_b32_e32 v97, 0xffff0000, v138
	v_pk_add_f32 v[86:87], v[86:87], v[94:95]
	v_pk_add_f32 v[84:85], v[84:85], v[92:93]
	v_pk_add_f32 v[94:95], v[80:81], v[96:97]
	v_mul_f32_e32 v80, v85, v85
	v_mul_f32_e32 v81, v87, v87
	v_fmac_f32_e32 v80, v84, v84
	v_fmac_f32_e32 v81, v86, v86
	v_lshlrev_b32_e32 v98, 16, v139
	v_and_b32_e32 v99, 0xffff0000, v139
	v_add_f32_e32 v80, v80, v81
	v_mul_f32_e32 v81, v95, v95
	v_pk_add_f32 v[92:93], v[82:83], v[98:99]
	v_fmac_f32_e32 v81, v94, v94
	v_add_f32_e32 v80, v81, v80
	v_mul_f32_e32 v81, v93, v93
	v_fmac_f32_e32 v81, v92, v92
	v_add_f32_e32 v80, v81, v80
	v_add_f32_e32 v83, v100, v80
	ds_bpermute_b32 v98, v186, v83
	v_lshl_add_u64 v[80:81], s[12:13], 0, v[180:181]
	v_lshl_add_u64 v[96:97], v[168:169], 1, v[80:81]
	ds_bpermute_b32 v240, v253, v88
	ds_bpermute_b32 v241, v253, v89
	ds_bpermute_b32 v242, v253, v90
	ds_bpermute_b32 v243, v253, v91
	v_lshl_add_u64 v[236:237], v[96:97], 0, v[250:251]
	s_waitcnt lgkmcnt(4)
	global_store_dwordx4 v[238:239], v[244:247], off offset:256
	v_cvt_pk_bf16_f32 v82, v84, v85
	s_waitcnt lgkmcnt(4)
	v_add_f32_e32 v80, v83, v98
	ds_bpermute_b32 v81, v187, v80
	v_cvt_pk_bf16_f32 v83, v86, v87
	v_cvt_pk_bf16_f32 v84, v94, v95
	v_cvt_pk_bf16_f32 v85, v92, v93
	ds_bpermute_b32 v244, v253, v82
	ds_bpermute_b32 v245, v253, v83
	ds_bpermute_b32 v246, v253, v84
	ds_bpermute_b32 v247, v253, v85
	v_lshl_add_u64 v[238:239], v[96:97], 0, v[250:251]
	s_waitcnt lgkmcnt(4)
	global_store_dwordx4 v[236:237], v[240:243], off
	s_and_saveexec_b64 s[34:35], s[4:5]
	s_cbranch_execz .LBB0_925
	v_lshlrev_b64 v[82:83], 6, v[178:179]
	v_lshl_add_u64 v[82:83], s[14:15], 0, v[82:83]
	v_lshl_add_u64 v[82:83], s[30:31], 2, v[82:83]
	s_lshl_b32 s8, s46, 2
	v_lshl_add_u64 v[82:83], v[82:83], 0, s[8:9]
	s_waitcnt lgkmcnt(4)
	v_add_f32_e32 v80, v80, v81
	global_store_dword v[82:83], v80, off
;     __device__ __forceinline__ void operator()(const f32x4 (&acc)[2][2][4][2], const Unit& u, int wr, int wc, int fr, int fq) const {
;     ...
;             u32x4 bw[4][2]; f32x4 bf[4][2][2];
; #pragma unroll
;             for (int m = 0; m < 4; ++m)
; #pragma unroll
;                 for (int bj = 0; bj < 2; ++bj) { const size_t off = (size_t)(row0 + ai * HALF + m * 16) * 1024 + col0 + bj * HALF;
;                     if (BASE_BF16) bw[m][bj] = *(const u32x4*)((const bf16_t*)base + off);
;                     else { bf[m][bj][0] = *(const f32x4*)((const float*)base + off); bf[m][bj][1] = *(const f32x4*)((const float*)base + off + 4); } }
;     ...
;             for (int m = 0; m < 4; ++m) {
;                 const int row = row0 + ai * HALF + m * 16; const size_t off = (size_t)row * 1024 + col0;
;                 float ss = 0.f;
; #pragma unroll
;                 for (int bj = 0; bj < 2; ++bj) {
;                     f32x4 b0, b1;
;                     if (BASE_BF16) { const u32x4 w = bw[m][bj];
;                         b0 = (f32x4){__builtin_bit_cast(float, w.x << 16), __builtin_bit_cast(float, w.x & 0xffff0000u), __builtin_bit_cast(float, w.y << 16), __builtin_bit_cast(float, w.y & 0xffff0000u)};
;                         b1 = (f32x4){__builtin_bit_cast(float, w.z << 16), __builtin_bit_cast(float, w.z & 0xffff0000u), __builtin_bit_cast(float, w.w << 16), __builtin_bit_cast(float, w.w & 0xffff0000u)}; }
;                     else { b0 = bf[m][bj][0]; b1 = bf[m][bj][1]; }
;                     const f32x4 v0 = acc[ai][bj][m][0] + b0, v1 = acc[ai][bj][m][1] + b1;
;                     ss += (v0[0] * v0[0] + v0[1] * v0[1]) + (v0[2] * v0[2] + v0[3] * v0[3]) + (v1[0] * v1[0] + v1[1] * v1[1]) + (v1[2] * v1[2] + v1[3] * v1[3]);
;                     if (OUT_BF16) { u32x4 w; w.x = cvt_pk_bf16(v0[0], v0[1]); w.y = cvt_pk_bf16(v0[2], v0[3]); w.z = cvt_pk_bf16(v1[0], v1[1]); w.w = cvt_pk_bf16(v1[2], v1[3]);
;                         *(u32x4*)((bf16_t*)out + off + bj * HALF) = w; }
;                     else { *(f32x4*)((float*)out + off + bj * HALF) = v0; *(f32x4*)((float*)out + off + bj * HALF + 4) = v1; }
;                 }
;                 ss += __shfl_xor(ss, 16); ss += __shfl_xor(ss, 32);
;                 if (fq == 0) sspart[(size_t)row * 16 + u.pn * 4 + wc] = ss;
.LBB0_925:
	s_or_b64 exec, exec, s[34:35]
	v_lshlrev_b32_e32 v80, 16, v132
	s_waitcnt lgkmcnt(0)
	v_and_b32_e32 v81, 0xffff0000, v132
	v_lshlrev_b32_e32 v82, 16, v133
	v_and_b32_e32 v83, 0xffff0000, v133
	v_lshlrev_b32_e32 v84, 16, v134
	v_and_b32_e32 v85, 0xffff0000, v134
	v_lshlrev_b32_e32 v86, 16, v135
	v_and_b32_e32 v87, 0xffff0000, v135
	v_pk_add_f32 v[78:79], v[78:79], v[82:83]
	v_pk_add_f32 v[76:77], v[76:77], v[80:81]
	v_pk_add_f32 v[80:81], v[74:75], v[86:87]
	v_pk_add_f32 v[74:75], v[72:73], v[84:85]
	v_mul_f32_e32 v72, v77, v77
	v_mul_f32_e32 v73, v79, v79
	v_fmac_f32_e32 v72, v76, v76
	v_fmac_f32_e32 v73, v78, v78
	v_add_f32_e32 v72, v72, v73
	v_mul_f32_e32 v73, v75, v75
	v_fmac_f32_e32 v73, v74, v74
	v_add_f32_e32 v72, v73, v72
	v_mul_f32_e32 v73, v81, v81
	v_fmac_f32_e32 v73, v80, v80
	v_add_f32_e32 v84, v73, v72
	v_cvt_pk_bf16_f32 v72, v76, v77
	v_cvt_pk_bf16_f32 v73, v78, v79
	v_lshlrev_b32_e32 v76, 16, v128
	v_and_b32_e32 v77, 0xffff0000, v128
	v_lshlrev_b32_e32 v78, 16, v129
	v_and_b32_e32 v79, 0xffff0000, v129
	v_cvt_pk_bf16_f32 v74, v74, v75
	v_cvt_pk_bf16_f32 v75, v80, v81
	v_lshlrev_b32_e32 v80, 16, v130
	v_and_b32_e32 v81, 0xffff0000, v130
	v_pk_add_f32 v[70:71], v[70:71], v[78:79]
	v_pk_add_f32 v[68:69], v[68:69], v[76:77]
	v_pk_add_f32 v[78:79], v[64:65], v[80:81]
	v_mul_f32_e32 v64, v69, v69
	v_mul_f32_e32 v65, v71, v71
	v_fmac_f32_e32 v64, v68, v68
	v_fmac_f32_e32 v65, v70, v70
	v_lshlrev_b32_e32 v82, 16, v131
	v_and_b32_e32 v83, 0xffff0000, v131
	v_add_f32_e32 v64, v64, v65
	v_mul_f32_e32 v65, v79, v79
	v_pk_add_f32 v[76:77], v[66:67], v[82:83]
	v_fmac_f32_e32 v65, v78, v78
	v_add_f32_e32 v64, v65, v64
	v_mul_f32_e32 v65, v77, v77
	v_fmac_f32_e32 v65, v76, v76
	v_add_f32_e32 v64, v65, v64
	v_add_f32_e32 v67, v84, v64
	ds_bpermute_b32 v82, v186, v67
	v_lshl_add_u64 v[64:65], s[12:13], 0, v[176:177]
	v_lshl_add_u64 v[80:81], v[168:169], 1, v[64:65]
	ds_bpermute_b32 v240, v253, v72
	ds_bpermute_b32 v241, v253, v73
	ds_bpermute_b32 v242, v253, v74
	ds_bpermute_b32 v243, v253, v75
	v_lshl_add_u64 v[236:237], v[80:81], 0, v[250:251]
	s_waitcnt lgkmcnt(4)
	global_store_dwordx4 v[238:239], v[244:247], off offset:256
	v_cvt_pk_bf16_f32 v66, v68, v69
	s_waitcnt lgkmcnt(4)
	v_add_f32_e32 v64, v67, v82
	ds_bpermute_b32 v65, v187, v64
	v_cvt_pk_bf16_f32 v67, v70, v71
	v_cvt_pk_bf16_f32 v68, v78, v79
	v_cvt_pk_bf16_f32 v69, v76, v77
	ds_bpermute_b32 v244, v253, v66
	ds_bpermute_b32 v245, v253, v67
	ds_bpermute_b32 v246, v253, v68
	ds_bpermute_b32 v247, v253, v69
	v_lshl_add_u64 v[238:239], v[80:81], 0, v[250:251]
	s_waitcnt lgkmcnt(4)
	global_store_dwordx4 v[236:237], v[240:243], off
	s_and_saveexec_b64 s[34:35], s[4:5]
	s_cbranch_execz .LBB0_927
	v_lshlrev_b64 v[66:67], 6, v[174:175]
	v_lshl_add_u64 v[66:67], s[14:15], 0, v[66:67]
	v_lshl_add_u64 v[66:67], s[30:31], 2, v[66:67]
	s_lshl_b32 s8, s46, 2
	v_lshl_add_u64 v[66:67], v[66:67], 0, s[8:9]
	s_waitcnt lgkmcnt(4)
	v_add_f32_e32 v64, v64, v65
	global_store_dword v[66:67], v64, off
.LBB0_927:
	s_or_b64 exec, exec, s[34:35]
	v_add_u32_e32 v100, 0x80, v172
	v_ashrrev_i32_e32 v101, 31, v100
	v_lshlrev_b64 v[110:111], 11, v[100:101]
	s_waitcnt lgkmcnt(0)
	v_lshl_add_u64 v[64:65], v[170:171], 0, v[110:111]
	global_load_dwordx4 v[102:105], v[64:65], off
	global_load_dwordx4 v[106:109], v[64:65], off offset:256
	v_add_u32_e32 v96, 0x90, v172
	v_add_u32_e32 v92, 0xa0, v172
	v_add_u32_e32 v88, 0xb0, v172
	v_ashrrev_i32_e32 v97, 31, v96
	v_ashrrev_i32_e32 v93, 31, v92
	v_ashrrev_i32_e32 v89, 31, v88
	v_lshlrev_b64 v[98:99], 11, v[96:97]
	v_lshlrev_b64 v[94:95], 11, v[92:93]
	v_lshlrev_b64 v[90:91], 11, v[88:89]
	v_lshl_add_u64 v[64:65], v[170:171], 0, v[98:99]
	v_lshl_add_u64 v[66:67], v[170:171], 0, v[94:95]
	v_lshl_add_u64 v[112:113], v[170:171], 0, v[90:91]
	global_load_dwordx4 v[84:87], v[64:65], off
	global_load_dwordx4 v[80:83], v[64:65], off offset:256
	global_load_dwordx4 v[76:79], v[66:67], off
	global_load_dwordx4 v[72:75], v[66:67], off offset:256
	global_load_dwordx4 v[68:71], v[112:113], off
	s_nop 0
	global_load_dwordx4 v[64:67], v[112:113], off offset:256
	s_waitcnt vmcnt(7)
	v_lshlrev_b32_e32 v112, 16, v102
	v_and_b32_e32 v113, 0xffff0000, v102
	v_lshlrev_b32_e32 v102, 16, v103
	v_and_b32_e32 v103, 0xffff0000, v103
	v_lshlrev_b32_e32 v114, 16, v104
	v_and_b32_e32 v115, 0xffff0000, v104
	v_lshlrev_b32_e32 v104, 16, v105
	v_and_b32_e32 v105, 0xffff0000, v105
	s_waitcnt vmcnt(6)
	v_lshlrev_b32_e32 v116, 16, v106
	v_and_b32_e32 v117, 0xffff0000, v106
	v_lshlrev_b32_e32 v106, 16, v107
	v_and_b32_e32 v107, 0xffff0000, v107
	v_lshlrev_b32_e32 v118, 16, v108
	v_and_b32_e32 v119, 0xffff0000, v108
	v_lshlrev_b32_e32 v108, 16, v109
	v_and_b32_e32 v109, 0xffff0000, v109
	v_pk_add_f32 v[62:63], v[62:63], v[102:103]
	v_pk_add_f32 v[60:61], v[60:61], v[112:113]
	v_pk_add_f32 v[58:59], v[58:59], v[104:105]
	v_pk_add_f32 v[56:57], v[56:57], v[114:115]
	v_pk_add_f32 v[54:55], v[54:55], v[106:107]
	v_pk_add_f32 v[52:53], v[52:53], v[116:117]
	v_pk_add_f32 v[102:103], v[50:51], v[108:109]
	v_pk_add_f32 v[104:105], v[48:49], v[118:119]
	v_mul_f32_e32 v106, v61, v61
	v_mul_f32_e32 v107, v63, v63
	v_mul_f32_e32 v108, v57, v57
	v_mul_f32_e32 v109, v59, v59
	v_cvt_pk_bf16_f32 v48, v60, v61
	v_cvt_pk_bf16_f32 v49, v62, v63
	v_cvt_pk_bf16_f32 v50, v56, v57
	v_cvt_pk_bf16_f32 v51, v58, v59
	v_mul_f32_e32 v57, v53, v53
	v_mul_f32_e32 v59, v55, v55
	v_mul_f32_e32 v61, v105, v105
	v_fmac_f32_e32 v106, v60, v60
	v_fmac_f32_e32 v107, v62, v62
	v_fmac_f32_e32 v57, v52, v52
	v_fmac_f32_e32 v59, v54, v54
	v_mul_f32_e32 v63, v103, v103
	v_fmac_f32_e32 v108, v56, v56
	v_fmac_f32_e32 v61, v104, v104
	v_add_f32_e32 v56, v106, v107
	v_add_f32_e32 v57, v57, v59
	v_fmac_f32_e32 v109, v58, v58
	v_fmac_f32_e32 v63, v102, v102
	v_add_f32_e32 v56, v108, v56
	v_add_f32_e32 v57, v61, v57
	v_add_f32_e32 v56, v109, v56
	v_add_f32_e32 v57, v63, v57
	v_add_f32_e32 v58, v56, v57
	ds_bpermute_b32 v59, v186, v58
	v_lshl_add_u64 v[56:57], s[12:13], 0, v[110:111]
	v_lshl_add_u64 v[56:57], v[168:169], 1, v[56:57]
	ds_bpermute_b32 v240, v253, v48
	ds_bpermute_b32 v241, v253, v49
	ds_bpermute_b32 v242, v253, v50
	ds_bpermute_b32 v243, v253, v51
	v_lshl_add_u64 v[236:237], v[56:57], 0, v[250:251]
	s_waitcnt lgkmcnt(4)
	global_store_dwordx4 v[238:239], v[244:247], off offset:256
	s_waitcnt lgkmcnt(4)
	s_nop 0
	v_add_f32_e32 v48, v58, v59
	ds_bpermute_b32 v49, v187, v48
	v_cvt_pk_bf16_f32 v50, v52, v53
	v_cvt_pk_bf16_f32 v51, v54, v55
	v_cvt_pk_bf16_f32 v52, v104, v105
	v_cvt_pk_bf16_f32 v53, v102, v103
	ds_bpermute_b32 v244, v253, v50
	ds_bpermute_b32 v245, v253, v51
	ds_bpermute_b32 v246, v253, v52
	ds_bpermute_b32 v247, v253, v53
	v_lshl_add_u64 v[238:239], v[56:57], 0, v[250:251]
	s_waitcnt lgkmcnt(4)
	global_store_dwordx4 v[236:237], v[240:243], off
	s_and_saveexec_b64 s[34:35], s[4:5]
	s_cbranch_execz .LBB0_929
; __device__ __forceinline__ unsigned cvt_pk_bf16(float lo, float hi) { unsigned r; asm volatile("v_cvt_pk_bf16_f32 %0, %1, %2" : "=v"(r) : "v"(lo), "v"(hi)); return r; }
;     __device__ __forceinline__ void operator()(const f32x4 (&acc)[2][2][4][2], const Unit& u, int wr, int wc, int fr, int fq) const {
;     ...
;             for (int m = 0; m < 4; ++m) {
;                 const int row = row0 + ai * HALF + m * 16; const size_t off = (size_t)row * 1024 + col0;
;                 float ss = 0.f;
; #pragma unroll
;                 for (int bj = 0; bj < 2; ++bj) {
;                     f32x4 b0, b1;
;                     if (BASE_BF16) { const u32x4 w = bw[m][bj];
;                         b0 = (f32x4){__builtin_bit_cast(float, w.x << 16), __builtin_bit_cast(float, w.x & 0xffff0000u), __builtin_bit_cast(float, w.y << 16), __builtin_bit_cast(float, w.y & 0xffff0000u)};
;                         b1 = (f32x4){__builtin_bit_cast(float, w.z << 16), __builtin_bit_cast(float, w.z & 0xffff0000u), __builtin_bit_cast(float, w.w << 16), __builtin_bit_cast(float, w.w & 0xffff0000u)}; }
;                     else { b0 = bf[m][bj][0]; b1 = bf[m][bj][1]; }
;                     const f32x4 v0 = acc[ai][bj][m][0] + b0, v1 = acc[ai][bj][m][1] + b1;
;                     ss += (v0[0] * v0[0] + v0[1] * v0[1]) + (v0[2] * v0[2] + v0[3] * v0[3]) + (v1[0] * v1[0] + v1[1] * v1[1]) + (v1[2] * v1[2] + v1[3] * v1[3]);
;                     if (OUT_BF16) { u32x4 w; w.x = cvt_pk_bf16(v0[0], v0[1]); w.y = cvt_pk_bf16(v0[2], v0[3]); w.z = cvt_pk_bf16(v1[0], v1[1]); w.w = cvt_pk_bf16(v1[2], v1[3]);
;                         *(u32x4*)((bf16_t*)out + off + bj * HALF) = w; }
;                     else { *(f32x4*)((float*)out + off + bj * HALF) = v0; *(f32x4*)((float*)out + off + bj * HALF + 4) = v1; }
;                 }
;                 ss += __shfl_xor(ss, 16); ss += __shfl_xor(ss, 32);
;                 if (fq == 0) sspart[(size_t)row * 16 + u.pn * 4 + wc] = ss;
	v_lshlrev_b64 v[50:51], 6, v[100:101]
	v_lshl_add_u64 v[50:51], s[14:15], 0, v[50:51]
	v_lshl_add_u64 v[50:51], s[30:31], 2, v[50:51]
	s_lshl_b32 s8, s46, 2
	v_lshl_add_u64 v[50:51], v[50:51], 0, s[8:9]
	s_waitcnt lgkmcnt(4)
	v_add_f32_e32 v48, v48, v49
	global_store_dword v[50:51], v48, off
.LBB0_929:
	s_or_b64 exec, exec, s[34:35]
	s_waitcnt vmcnt(7)
	v_lshlrev_b32_e32 v48, 16, v84
	s_waitcnt lgkmcnt(0)
	v_and_b32_e32 v49, 0xffff0000, v84
	v_lshlrev_b32_e32 v50, 16, v85
	v_and_b32_e32 v51, 0xffff0000, v85
	v_lshlrev_b32_e32 v52, 16, v86
	v_and_b32_e32 v53, 0xffff0000, v86
	v_lshlrev_b32_e32 v54, 16, v87
	v_and_b32_e32 v55, 0xffff0000, v87
	v_pk_add_f32 v[46:47], v[46:47], v[50:51]
	v_pk_add_f32 v[44:45], v[44:45], v[48:49]
	v_pk_add_f32 v[48:49], v[42:43], v[54:55]
	v_pk_add_f32 v[42:43], v[40:41], v[52:53]
	v_mul_f32_e32 v40, v45, v45
	v_mul_f32_e32 v41, v47, v47
	v_fmac_f32_e32 v40, v44, v44
	v_fmac_f32_e32 v41, v46, v46
	v_add_f32_e32 v40, v40, v41
	v_mul_f32_e32 v41, v43, v43
	v_fmac_f32_e32 v41, v42, v42
	v_add_f32_e32 v40, v41, v40
	v_mul_f32_e32 v41, v49, v49
	v_fmac_f32_e32 v41, v48, v48
	v_add_f32_e32 v52, v41, v40
	v_cvt_pk_bf16_f32 v40, v44, v45
	v_cvt_pk_bf16_f32 v41, v46, v47
	s_waitcnt vmcnt(6)
	v_lshlrev_b32_e32 v44, 16, v80
	v_and_b32_e32 v45, 0xffff0000, v80
	v_lshlrev_b32_e32 v46, 16, v81
	v_and_b32_e32 v47, 0xffff0000, v81
	v_cvt_pk_bf16_f32 v42, v42, v43
	v_cvt_pk_bf16_f32 v43, v48, v49
	v_lshlrev_b32_e32 v48, 16, v82
	v_and_b32_e32 v49, 0xffff0000, v82
	v_pk_add_f32 v[38:39], v[38:39], v[46:47]
	v_pk_add_f32 v[36:37], v[36:37], v[44:45]
	v_pk_add_f32 v[46:47], v[32:33], v[48:49]
	v_mul_f32_e32 v32, v37, v37
	v_mul_f32_e32 v33, v39, v39
	v_fmac_f32_e32 v32, v36, v36
	v_fmac_f32_e32 v33, v38, v38
	v_lshlrev_b32_e32 v50, 16, v83
	v_and_b32_e32 v51, 0xffff0000, v83
	v_add_f32_e32 v32, v32, v33
	v_mul_f32_e32 v33, v47, v47
	v_pk_add_f32 v[44:45], v[34:35], v[50:51]
	v_fmac_f32_e32 v33, v46, v46
	v_add_f32_e32 v32, v33, v32
	v_mul_f32_e32 v33, v45, v45
	v_fmac_f32_e32 v33, v44, v44
	v_add_f32_e32 v32, v33, v32
	v_add_f32_e32 v35, v52, v32
	ds_bpermute_b32 v50, v186, v35
	v_lshl_add_u64 v[32:33], s[12:13], 0, v[98:99]
	v_lshl_add_u64 v[48:49], v[168:169], 1, v[32:33]
	ds_bpermute_b32 v240, v253, v40
	ds_bpermute_b32 v241, v253, v41
	ds_bpermute_b32 v242, v253, v42
	ds_bpermute_b32 v243, v253, v43
	v_lshl_add_u64 v[236:237], v[48:49], 0, v[250:251]
	s_waitcnt lgkmcnt(4)
	global_store_dwordx4 v[238:239], v[244:247], off offset:256
	v_cvt_pk_bf16_f32 v34, v36, v37
	s_waitcnt lgkmcnt(4)
	v_add_f32_e32 v32, v35, v50
	ds_bpermute_b32 v33, v187, v32
	v_cvt_pk_bf16_f32 v35, v38, v39
	v_cvt_pk_bf16_f32 v36, v46, v47
	v_cvt_pk_bf16_f32 v37, v44, v45
	ds_bpermute_b32 v244, v253, v34
	ds_bpermute_b32 v245, v253, v35
	ds_bpermute_b32 v246, v253, v36
	ds_bpermute_b32 v247, v253, v37
	v_lshl_add_u64 v[238:239], v[48:49], 0, v[250:251]
	s_waitcnt lgkmcnt(4)
	global_store_dwordx4 v[236:237], v[240:243], off
	s_and_saveexec_b64 s[34:35], s[4:5]
	s_cbranch_execz .LBB0_931
	v_lshlrev_b64 v[34:35], 6, v[96:97]
	v_lshl_add_u64 v[34:35], s[14:15], 0, v[34:35]
	v_lshl_add_u64 v[34:35], s[30:31], 2, v[34:35]
	s_lshl_b32 s8, s46, 2
	v_lshl_add_u64 v[34:35], v[34:35], 0, s[8:9]
	s_waitcnt lgkmcnt(4)
	v_add_f32_e32 v32, v32, v33
	global_store_dword v[34:35], v32, off
; __device__ __forceinline__ unsigned cvt_pk_bf16(float lo, float hi) { unsigned r; asm volatile("v_cvt_pk_bf16_f32 %0, %1, %2" : "=v"(r) : "v"(lo), "v"(hi)); return r; }
;     __device__ __forceinline__ void operator()(const f32x4 (&acc)[2][2][4][2], const Unit& u, int wr, int wc, int fr, int fq) const {
;     ...
;             for (int m = 0; m < 4; ++m) {
;                 const int row = row0 + ai * HALF + m * 16; const size_t off = (size_t)row * 1024 + col0;
;                 float ss = 0.f;
; #pragma unroll
;                 for (int bj = 0; bj < 2; ++bj) {
;                     f32x4 b0, b1;
;                     if (BASE_BF16) { const u32x4 w = bw[m][bj];
;                         b0 = (f32x4){__builtin_bit_cast(float, w.x << 16), __builtin_bit_cast(float, w.x & 0xffff0000u), __builtin_bit_cast(float, w.y << 16), __builtin_bit_cast(float, w.y & 0xffff0000u)};
;                         b1 = (f32x4){__builtin_bit_cast(float, w.z << 16), __builtin_bit_cast(float, w.z & 0xffff0000u), __builtin_bit_cast(float, w.w << 16), __builtin_bit_cast(float, w.w & 0xffff0000u)}; }
;                     else { b0 = bf[m][bj][0]; b1 = bf[m][bj][1]; }
;                     const f32x4 v0 = acc[ai][bj][m][0] + b0, v1 = acc[ai][bj][m][1] + b1;
;                     ss += (v0[0] * v0[0] + v0[1] * v0[1]) + (v0[2] * v0[2] + v0[3] * v0[3]) + (v1[0] * v1[0] + v1[1] * v1[1]) + (v1[2] * v1[2] + v1[3] * v1[3]);
;                     if (OUT_BF16) { u32x4 w; w.x = cvt_pk_bf16(v0[0], v0[1]); w.y = cvt_pk_bf16(v0[2], v0[3]); w.z = cvt_pk_bf16(v1[0], v1[1]); w.w = cvt_pk_bf16(v1[2], v1[3]);
;                         *(u32x4*)((bf16_t*)out + off + bj * HALF) = w; }
;                     else { *(f32x4*)((float*)out + off + bj * HALF) = v0; *(f32x4*)((float*)out + off + bj * HALF + 4) = v1; }
;                 }
;                 ss += __shfl_xor(ss, 16); ss += __shfl_xor(ss, 32);
;                 if (fq == 0) sspart[(size_t)row * 16 + u.pn * 4 + wc] = ss;
.LBB0_931:
	s_or_b64 exec, exec, s[34:35]
	s_waitcnt vmcnt(7)
	v_lshlrev_b32_e32 v32, 16, v76
	s_waitcnt lgkmcnt(0)
	v_and_b32_e32 v33, 0xffff0000, v76
	v_lshlrev_b32_e32 v34, 16, v77
	v_and_b32_e32 v35, 0xffff0000, v77
	v_lshlrev_b32_e32 v36, 16, v78
	v_and_b32_e32 v37, 0xffff0000, v78
	v_lshlrev_b32_e32 v38, 16, v79
	v_and_b32_e32 v39, 0xffff0000, v79
	v_pk_add_f32 v[30:31], v[30:31], v[34:35]
	v_pk_add_f32 v[28:29], v[28:29], v[32:33]
	v_pk_add_f32 v[32:33], v[26:27], v[38:39]
	v_pk_add_f32 v[26:27], v[24:25], v[36:37]
	v_mul_f32_e32 v24, v29, v29
	v_mul_f32_e32 v25, v31, v31
	v_fmac_f32_e32 v24, v28, v28
	v_fmac_f32_e32 v25, v30, v30
	v_add_f32_e32 v24, v24, v25
	v_mul_f32_e32 v25, v27, v27
	v_fmac_f32_e32 v25, v26, v26
	v_add_f32_e32 v24, v25, v24
	v_mul_f32_e32 v25, v33, v33
	v_fmac_f32_e32 v25, v32, v32
	v_add_f32_e32 v36, v25, v24
	v_cvt_pk_bf16_f32 v24, v28, v29
	v_cvt_pk_bf16_f32 v25, v30, v31
	s_waitcnt vmcnt(6)
	v_lshlrev_b32_e32 v28, 16, v72
	v_and_b32_e32 v29, 0xffff0000, v72
	v_lshlrev_b32_e32 v30, 16, v73
	v_and_b32_e32 v31, 0xffff0000, v73
	v_cvt_pk_bf16_f32 v26, v26, v27
	v_cvt_pk_bf16_f32 v27, v32, v33
	v_lshlrev_b32_e32 v32, 16, v74
	v_and_b32_e32 v33, 0xffff0000, v74
	v_pk_add_f32 v[22:23], v[22:23], v[30:31]
	v_pk_add_f32 v[20:21], v[20:21], v[28:29]
	v_pk_add_f32 v[30:31], v[16:17], v[32:33]
	v_mul_f32_e32 v16, v21, v21
	v_mul_f32_e32 v17, v23, v23
	v_fmac_f32_e32 v16, v20, v20
	v_fmac_f32_e32 v17, v22, v22
	v_lshlrev_b32_e32 v34, 16, v75
	v_and_b32_e32 v35, 0xffff0000, v75
	v_add_f32_e32 v16, v16, v17
	v_mul_f32_e32 v17, v31, v31
	v_pk_add_f32 v[28:29], v[18:19], v[34:35]
	v_fmac_f32_e32 v17, v30, v30
	v_add_f32_e32 v16, v17, v16
	v_mul_f32_e32 v17, v29, v29
	v_fmac_f32_e32 v17, v28, v28
	v_add_f32_e32 v16, v17, v16
	v_add_f32_e32 v19, v36, v16
	ds_bpermute_b32 v34, v186, v19
	v_lshl_add_u64 v[16:17], s[12:13], 0, v[94:95]
	v_lshl_add_u64 v[32:33], v[168:169], 1, v[16:17]
	ds_bpermute_b32 v240, v253, v24
	ds_bpermute_b32 v241, v253, v25
	ds_bpermute_b32 v242, v253, v26
	ds_bpermute_b32 v243, v253, v27
	v_lshl_add_u64 v[236:237], v[32:33], 0, v[250:251]
	s_waitcnt lgkmcnt(4)
	global_store_dwordx4 v[238:239], v[244:247], off offset:256
	v_cvt_pk_bf16_f32 v18, v20, v21
	s_waitcnt lgkmcnt(4)
	v_add_f32_e32 v16, v19, v34
	ds_bpermute_b32 v17, v187, v16
	v_cvt_pk_bf16_f32 v19, v22, v23
	v_cvt_pk_bf16_f32 v20, v30, v31
	v_cvt_pk_bf16_f32 v21, v28, v29
	ds_bpermute_b32 v244, v253, v18
	ds_bpermute_b32 v245, v253, v19
	ds_bpermute_b32 v246, v253, v20
	ds_bpermute_b32 v247, v253, v21
	v_lshl_add_u64 v[238:239], v[32:33], 0, v[250:251]
	s_waitcnt lgkmcnt(4)
	global_store_dwordx4 v[236:237], v[240:243], off
	s_and_saveexec_b64 s[34:35], s[4:5]
	s_cbranch_execz .LBB0_933
	v_lshlrev_b64 v[18:19], 6, v[92:93]
	v_lshl_add_u64 v[18:19], s[14:15], 0, v[18:19]
	v_lshl_add_u64 v[18:19], s[30:31], 2, v[18:19]
	s_lshl_b32 s8, s46, 2
	v_lshl_add_u64 v[18:19], v[18:19], 0, s[8:9]
	s_waitcnt lgkmcnt(4)
	v_add_f32_e32 v16, v16, v17
	global_store_dword v[18:19], v16, off
.LBB0_933:
	s_or_b64 exec, exec, s[34:35]
	s_waitcnt vmcnt(7)
	v_lshlrev_b32_e32 v16, 16, v68
	s_waitcnt lgkmcnt(0)
	v_and_b32_e32 v17, 0xffff0000, v68
	v_lshlrev_b32_e32 v18, 16, v69
	v_and_b32_e32 v19, 0xffff0000, v69
	v_lshlrev_b32_e32 v20, 16, v70
	v_and_b32_e32 v21, 0xffff0000, v70
	v_lshlrev_b32_e32 v22, 16, v71
	v_and_b32_e32 v23, 0xffff0000, v71
	v_pk_add_f32 v[14:15], v[14:15], v[18:19]
	v_pk_add_f32 v[12:13], v[12:13], v[16:17]
	v_pk_add_f32 v[16:17], v[10:11], v[22:23]
	v_pk_add_f32 v[10:11], v[8:9], v[20:21]
	v_mul_f32_e32 v8, v13, v13
	v_mul_f32_e32 v9, v15, v15
	v_fmac_f32_e32 v8, v12, v12
	v_fmac_f32_e32 v9, v14, v14
	v_add_f32_e32 v8, v8, v9
	v_mul_f32_e32 v9, v11, v11
	v_fmac_f32_e32 v9, v10, v10
	v_add_f32_e32 v8, v9, v8
	v_mul_f32_e32 v9, v17, v17
	v_fmac_f32_e32 v9, v16, v16
	v_add_f32_e32 v20, v9, v8
	v_cvt_pk_bf16_f32 v8, v12, v13
	v_cvt_pk_bf16_f32 v9, v14, v15
	s_waitcnt vmcnt(6)
	v_lshlrev_b32_e32 v12, 16, v64
	v_and_b32_e32 v13, 0xffff0000, v64
	v_lshlrev_b32_e32 v14, 16, v65
	v_and_b32_e32 v15, 0xffff0000, v65
	v_cvt_pk_bf16_f32 v10, v10, v11
	v_cvt_pk_bf16_f32 v11, v16, v17
	v_lshlrev_b32_e32 v16, 16, v66
	v_and_b32_e32 v17, 0xffff0000, v66
	v_pk_add_f32 v[6:7], v[6:7], v[14:15]
	v_pk_add_f32 v[4:5], v[4:5], v[12:13]
	v_pk_add_f32 v[14:15], v[0:1], v[16:17]
	v_mul_f32_e32 v0, v5, v5
	v_mul_f32_e32 v1, v7, v7
	v_fmac_f32_e32 v0, v4, v4
	v_fmac_f32_e32 v1, v6, v6
	v_lshlrev_b32_e32 v18, 16, v67
	v_and_b32_e32 v19, 0xffff0000, v67
	v_add_f32_e32 v0, v0, v1
	v_mul_f32_e32 v1, v15, v15
	v_pk_add_f32 v[12:13], v[2:3], v[18:19]
	v_fmac_f32_e32 v1, v14, v14
	v_add_f32_e32 v0, v1, v0
	v_mul_f32_e32 v1, v13, v13
	v_fmac_f32_e32 v1, v12, v12
	v_add_f32_e32 v0, v1, v0
	v_add_f32_e32 v3, v20, v0
	ds_bpermute_b32 v18, v186, v3
	v_lshl_add_u64 v[0:1], s[12:13], 0, v[90:91]
	v_lshl_add_u64 v[16:17], v[168:169], 1, v[0:1]
	ds_bpermute_b32 v240, v253, v8
	ds_bpermute_b32 v241, v253, v9
	ds_bpermute_b32 v242, v253, v10
	ds_bpermute_b32 v243, v253, v11
	v_lshl_add_u64 v[236:237], v[16:17], 0, v[250:251]
	s_waitcnt lgkmcnt(4)
	global_store_dwordx4 v[238:239], v[244:247], off offset:256
	v_cvt_pk_bf16_f32 v2, v4, v5
	s_waitcnt lgkmcnt(4)
	v_add_f32_e32 v0, v3, v18
	ds_bpermute_b32 v1, v187, v0
	v_cvt_pk_bf16_f32 v3, v6, v7
	v_cvt_pk_bf16_f32 v4, v14, v15
	v_cvt_pk_bf16_f32 v5, v12, v13
	ds_bpermute_b32 v244, v253, v2
	ds_bpermute_b32 v245, v253, v3
	ds_bpermute_b32 v246, v253, v4
	ds_bpermute_b32 v247, v253, v5
	v_lshl_add_u64 v[238:239], v[16:17], 0, v[250:251]
	s_waitcnt lgkmcnt(4)
	global_store_dwordx4 v[236:237], v[240:243], off
	s_waitcnt lgkmcnt(0)
	global_store_dwordx4 v[238:239], v[244:247], off offset:256
	s_and_saveexec_b64 s[34:35], s[4:5]
	s_cbranch_execz .LBB0_935
	v_lshlrev_b64 v[2:3], 6, v[88:89]
	v_lshl_add_u64 v[2:3], s[14:15], 0, v[2:3]
	v_lshl_add_u64 v[2:3], s[30:31], 2, v[2:3]
	s_lshl_b32 s8, s46, 2
	v_lshl_add_u64 v[2:3], v[2:3], 0, s[8:9]
	s_waitcnt lgkmcnt(0)
	v_add_f32_e32 v0, v0, v1
	global_store_dword v[2:3], v0, off

; __device__ __forceinline__ unsigned cvt_pk_bf16(float lo, float hi) { unsigned r; asm volatile("v_cvt_pk_bf16_f32 %0, %1, %2" : "=v"(r) : "v"(lo), "v"(hi)); return r; }
;     __device__ __forceinline__ void operator()(const f32x4 (&acc)[2][2][4][2], const Unit& u, int wr, int wc, int fr, int fq) const {
;     ...
;                 for (int bj = 0; bj < 2; ++bj) { const size_t off = (size_t)(row0 + ai * HALF + m * 16) * 1024 + col0 + bj * HALF;
;                     if (BASE_BF16) bw[m][bj] = *(const u32x4*)((const bf16_t*)base + off);
;                     else { bf[m][bj][0] = *(const f32x4*)((const float*)base + off); bf[m][bj][1] = *(const f32x4*)((const float*)base + off + 4); } }
; #pragma unroll
;             for (int m = 0; m < 4; ++m) {
;                 const int row = row0 + ai * HALF + m * 16; const size_t off = (size_t)row * 1024 + col0;
;                 float ss = 0.f;
; #pragma unroll
;                 for (int bj = 0; bj < 2; ++bj) {
;                     f32x4 b0, b1;
;                     if (BASE_BF16) { const u32x4 w = bw[m][bj];
;                         b0 = (f32x4){__builtin_bit_cast(float, w.x << 16), __builtin_bit_cast(float, w.x & 0xffff0000u), __builtin_bit_cast(float, w.y << 16), __builtin_bit_cast(float, w.y & 0xffff0000u)};
;                         b1 = (f32x4){__builtin_bit_cast(float, w.z << 16), __builtin_bit_cast(float, w.z & 0xffff0000u), __builtin_bit_cast(float, w.w << 16), __builtin_bit_cast(float, w.w & 0xffff0000u)}; }
;                     else { b0 = bf[m][bj][0]; b1 = bf[m][bj][1]; }
;                     const f32x4 v0 = acc[ai][bj][m][0] + b0, v1 = acc[ai][bj][m][1] + b1;
;                     ss += (v0[0] * v0[0] + v0[1] * v0[1]) + (v0[2] * v0[2] + v0[3] * v0[3]) + (v1[0] * v1[0] + v1[1] * v1[1]) + (v1[2] * v1[2] + v1[3] * v1[3]);
;                     if (OUT_BF16) { u32x4 w; w.x = cvt_pk_bf16(v0[0], v0[1]); w.y = cvt_pk_bf16(v0[2], v0[3]); w.z = cvt_pk_bf16(v1[0], v1[1]); w.w = cvt_pk_bf16(v1[2], v1[3]);
;                         *(u32x4*)((bf16_t*)out + off + bj * HALF) = w; }
;                     else { *(f32x4*)((float*)out + off + bj * HALF) = v0; *(f32x4*)((float*)out + off + bj * HALF + 4) = v1; }
;                 }
;                 ss += __shfl_xor(ss, 16); ss += __shfl_xor(ss, 32);
;                 if (fq == 0) sspart[(size_t)row * 16 + u.pn * 4 + wc] = ss;
.LBB0_1218:
	v_lshl_or_b32 v168, s8, 8, v190
	v_lshl_add_u32 v172, s34, 8, v188
	v_ashrrev_i32_e32 v169, 31, v168
	v_lshlrev_b64 v[202:203], 1, v[168:169]
	v_ashrrev_i32_e32 v173, 31, v172
	v_lshl_add_u64 v[170:171], s[12:13], 0, v[202:203]
	v_lshlrev_b64 v[204:205], 11, v[172:173]
	v_lshl_add_u64 v[128:129], v[170:171], 0, v[204:205]
	global_load_dwordx4 v[194:197], v[128:129], off
	global_load_dwordx4 v[198:201], v[128:129], off offset:256
	v_or_b32_e32 v182, 16, v172
	v_or_b32_e32 v178, 32, v172
	v_or_b32_e32 v174, 48, v172
	v_ashrrev_i32_e32 v183, 31, v182
	v_ashrrev_i32_e32 v179, 31, v178
	v_ashrrev_i32_e32 v175, 31, v174
	v_lshlrev_b64 v[184:185], 11, v[182:183]
	v_lshlrev_b64 v[180:181], 11, v[178:179]
	v_lshlrev_b64 v[176:177], 11, v[174:175]
	v_lshl_add_u64 v[128:129], v[170:171], 0, v[184:185]
	v_lshl_add_u64 v[130:131], v[170:171], 0, v[180:181]
	v_lshl_add_u64 v[206:207], v[170:171], 0, v[176:177]
	global_load_dwordx4 v[148:151], v[128:129], off
	global_load_dwordx4 v[144:147], v[128:129], off offset:256
	global_load_dwordx4 v[140:143], v[130:131], off
	global_load_dwordx4 v[136:139], v[130:131], off offset:256
	global_load_dwordx4 v[132:135], v[206:207], off
	s_nop 0
	global_load_dwordx4 v[128:131], v[206:207], off offset:256
	s_lshl_b32 s34, s8, 2
	s_ashr_i32 s35, s34, 31
	s_waitcnt vmcnt(0)
	v_lshlrev_b32_e32 v206, 16, v194
	v_and_b32_e32 v207, 0xffff0000, v194
	v_lshlrev_b32_e32 v194, 16, v195
	v_and_b32_e32 v195, 0xffff0000, v195
	v_lshlrev_b32_e32 v208, 16, v196
	v_and_b32_e32 v209, 0xffff0000, v196
	v_lshlrev_b32_e32 v196, 16, v197
	v_and_b32_e32 v197, 0xffff0000, v197
	v_lshlrev_b32_e32 v210, 16, v198
	v_and_b32_e32 v211, 0xffff0000, v198
	v_lshlrev_b32_e32 v198, 16, v199
	v_and_b32_e32 v199, 0xffff0000, v199
	v_lshlrev_b32_e32 v214, 16, v200
	v_and_b32_e32 v215, 0xffff0000, v200
	v_lshlrev_b32_e32 v200, 16, v201
	v_and_b32_e32 v201, 0xffff0000, v201
	v_pk_add_f32 v[126:127], v[126:127], v[194:195]
	v_pk_add_f32 v[124:125], v[124:125], v[206:207]
	v_pk_add_f32 v[122:123], v[122:123], v[196:197]
	v_pk_add_f32 v[120:121], v[120:121], v[208:209]
	v_pk_add_f32 v[118:119], v[118:119], v[198:199]
	v_pk_add_f32 v[116:117], v[116:117], v[210:211]
	v_pk_add_f32 v[194:195], v[114:115], v[200:201]
	v_pk_add_f32 v[196:197], v[112:113], v[214:215]
	v_mul_f32_e32 v198, v125, v125
	v_mul_f32_e32 v199, v127, v127
	v_mul_f32_e32 v200, v121, v121
	v_mul_f32_e32 v201, v123, v123
	v_cvt_pk_bf16_f32 v112, v124, v125
	v_cvt_pk_bf16_f32 v113, v126, v127
	v_cvt_pk_bf16_f32 v114, v120, v121
	v_cvt_pk_bf16_f32 v115, v122, v123
	v_mul_f32_e32 v121, v117, v117
	v_mul_f32_e32 v123, v119, v119
	v_mul_f32_e32 v125, v197, v197
	v_fmac_f32_e32 v198, v124, v124
	v_fmac_f32_e32 v199, v126, v126
	v_fmac_f32_e32 v121, v116, v116
	v_fmac_f32_e32 v123, v118, v118
	v_mul_f32_e32 v127, v195, v195
	v_fmac_f32_e32 v200, v120, v120
	v_fmac_f32_e32 v125, v196, v196
	v_add_f32_e32 v120, v198, v199
	v_add_f32_e32 v121, v121, v123
	v_fmac_f32_e32 v201, v122, v122
	v_fmac_f32_e32 v127, v194, v194
	v_add_f32_e32 v120, v200, v120
	v_add_f32_e32 v121, v125, v121
	v_add_f32_e32 v120, v201, v120
	v_add_f32_e32 v121, v127, v121
	v_add_f32_e32 v122, v120, v121
	ds_bpermute_b32 v123, v186, v122
	v_lshl_add_u64 v[120:121], s[14:15], 0, v[204:205]
	v_lshl_add_u64 v[120:121], v[120:121], 0, v[202:203]
	ds_bpermute_b32 v240, v253, v112
	ds_bpermute_b32 v241, v253, v113
	ds_bpermute_b32 v242, v253, v114
	ds_bpermute_b32 v243, v253, v115
	v_lshl_add_u64 v[236:237], v[120:121], 0, v[250:251]
	s_waitcnt lgkmcnt(4)
	s_nop 0
	v_add_f32_e32 v112, v122, v123
	ds_bpermute_b32 v113, v187, v112
	v_cvt_pk_bf16_f32 v114, v116, v117
	v_cvt_pk_bf16_f32 v115, v118, v119
	v_cvt_pk_bf16_f32 v116, v196, v197
	v_cvt_pk_bf16_f32 v117, v194, v195
	ds_bpermute_b32 v244, v253, v114
	ds_bpermute_b32 v245, v253, v115
	ds_bpermute_b32 v246, v253, v116
	ds_bpermute_b32 v247, v253, v117
	v_lshl_add_u64 v[238:239], v[120:121], 0, v[250:251]
	s_waitcnt lgkmcnt(4)
	global_store_dwordx4 v[236:237], v[240:243], off
	s_and_saveexec_b64 s[36:37], s[4:5]
	s_cbranch_execz .LBB0_1220
	v_lshlrev_b64 v[114:115], 6, v[172:173]
	v_lshl_add_u64 v[114:115], s[16:17], 0, v[114:115]
	v_lshl_add_u64 v[114:115], s[34:35], 2, v[114:115]
	s_lshl_b32 s8, s48, 2
	v_lshl_add_u64 v[114:115], v[114:115], 0, s[8:9]
	s_waitcnt lgkmcnt(4)
	v_add_f32_e32 v112, v112, v113
	global_store_dword v[114:115], v112, off
; __device__ __forceinline__ unsigned cvt_pk_bf16(float lo, float hi) { unsigned r; asm volatile("v_cvt_pk_bf16_f32 %0, %1, %2" : "=v"(r) : "v"(lo), "v"(hi)); return r; }
;     __device__ __forceinline__ void operator()(const f32x4 (&acc)[2][2][4][2], const Unit& u, int wr, int wc, int fr, int fq) const {
;     ...
;             for (int m = 0; m < 4; ++m) {
;                 const int row = row0 + ai * HALF + m * 16; const size_t off = (size_t)row * 1024 + col0;
;                 float ss = 0.f;
; #pragma unroll
;                 for (int bj = 0; bj < 2; ++bj) {
;                     f32x4 b0, b1;
;                     if (BASE_BF16) { const u32x4 w = bw[m][bj];
;                         b0 = (f32x4){__builtin_bit_cast(float, w.x << 16), __builtin_bit_cast(float, w.x & 0xffff0000u), __builtin_bit_cast(float, w.y << 16), __builtin_bit_cast(float, w.y & 0xffff0000u)};
;                         b1 = (f32x4){__builtin_bit_cast(float, w.z << 16), __builtin_bit_cast(float, w.z & 0xffff0000u), __builtin_bit_cast(float, w.w << 16), __builtin_bit_cast(float, w.w & 0xffff0000u)}; }
;                     else { b0 = bf[m][bj][0]; b1 = bf[m][bj][1]; }
;                     const f32x4 v0 = acc[ai][bj][m][0] + b0, v1 = acc[ai][bj][m][1] + b1;
;                     ss += (v0[0] * v0[0] + v0[1] * v0[1]) + (v0[2] * v0[2] + v0[3] * v0[3]) + (v1[0] * v1[0] + v1[1] * v1[1]) + (v1[2] * v1[2] + v1[3] * v1[3]);
;                     if (OUT_BF16) { u32x4 w; w.x = cvt_pk_bf16(v0[0], v0[1]); w.y = cvt_pk_bf16(v0[2], v0[3]); w.z = cvt_pk_bf16(v1[0], v1[1]); w.w = cvt_pk_bf16(v1[2], v1[3]);
;                         *(u32x4*)((bf16_t*)out + off + bj * HALF) = w; }
;                     else { *(f32x4*)((float*)out + off + bj * HALF) = v0; *(f32x4*)((float*)out + off + bj * HALF + 4) = v1; }
;                 }
;                 ss += __shfl_xor(ss, 16); ss += __shfl_xor(ss, 32);
;                 if (fq == 0) sspart[(size_t)row * 16 + u.pn * 4 + wc] = ss;
.LBB0_1220:
	s_or_b64 exec, exec, s[36:37]
	v_lshlrev_b32_e32 v112, 16, v148
	s_waitcnt lgkmcnt(0)
	v_and_b32_e32 v113, 0xffff0000, v148
	v_lshlrev_b32_e32 v114, 16, v149
	v_and_b32_e32 v115, 0xffff0000, v149
	v_lshlrev_b32_e32 v116, 16, v150
	v_and_b32_e32 v117, 0xffff0000, v150
	v_lshlrev_b32_e32 v118, 16, v151
	v_and_b32_e32 v119, 0xffff0000, v151
	v_pk_add_f32 v[110:111], v[110:111], v[114:115]
	v_pk_add_f32 v[108:109], v[108:109], v[112:113]
	v_pk_add_f32 v[112:113], v[106:107], v[118:119]
	v_pk_add_f32 v[106:107], v[104:105], v[116:117]
	v_mul_f32_e32 v104, v109, v109
	v_mul_f32_e32 v105, v111, v111
	v_fmac_f32_e32 v104, v108, v108
	v_fmac_f32_e32 v105, v110, v110
	v_add_f32_e32 v104, v104, v105
	v_mul_f32_e32 v105, v107, v107
	v_fmac_f32_e32 v105, v106, v106
	v_add_f32_e32 v104, v105, v104
	v_mul_f32_e32 v105, v113, v113
	v_fmac_f32_e32 v105, v112, v112
	v_add_f32_e32 v116, v105, v104
	v_cvt_pk_bf16_f32 v104, v108, v109
	v_cvt_pk_bf16_f32 v105, v110, v111
	v_lshlrev_b32_e32 v108, 16, v144
	v_and_b32_e32 v109, 0xffff0000, v144
	v_lshlrev_b32_e32 v110, 16, v145
	v_and_b32_e32 v111, 0xffff0000, v145
	v_cvt_pk_bf16_f32 v106, v106, v107
	v_cvt_pk_bf16_f32 v107, v112, v113
	v_lshlrev_b32_e32 v112, 16, v146
	v_and_b32_e32 v113, 0xffff0000, v146
	v_pk_add_f32 v[102:103], v[102:103], v[110:111]
	v_pk_add_f32 v[100:101], v[100:101], v[108:109]
	v_pk_add_f32 v[110:111], v[96:97], v[112:113]
	v_mul_f32_e32 v96, v101, v101
	v_mul_f32_e32 v97, v103, v103
	v_fmac_f32_e32 v96, v100, v100
	v_fmac_f32_e32 v97, v102, v102
	v_lshlrev_b32_e32 v114, 16, v147
	v_and_b32_e32 v115, 0xffff0000, v147
	v_add_f32_e32 v96, v96, v97
	v_mul_f32_e32 v97, v111, v111
	v_pk_add_f32 v[108:109], v[98:99], v[114:115]
	v_fmac_f32_e32 v97, v110, v110
	v_add_f32_e32 v96, v97, v96
	v_mul_f32_e32 v97, v109, v109
	v_fmac_f32_e32 v97, v108, v108
	v_add_f32_e32 v96, v97, v96
	v_add_f32_e32 v99, v116, v96
	ds_bpermute_b32 v114, v186, v99
	v_lshl_add_u64 v[96:97], s[14:15], 0, v[184:185]
	v_lshl_add_u64 v[112:113], v[168:169], 1, v[96:97]
	ds_bpermute_b32 v240, v253, v104
	ds_bpermute_b32 v241, v253, v105
	ds_bpermute_b32 v242, v253, v106
	ds_bpermute_b32 v243, v253, v107
	v_lshl_add_u64 v[236:237], v[112:113], 0, v[250:251]
	s_waitcnt lgkmcnt(4)
	global_store_dwordx4 v[238:239], v[244:247], off offset:256
	v_cvt_pk_bf16_f32 v98, v100, v101
	s_waitcnt lgkmcnt(4)
	v_add_f32_e32 v96, v99, v114
	ds_bpermute_b32 v97, v187, v96
	v_cvt_pk_bf16_f32 v99, v102, v103
	v_cvt_pk_bf16_f32 v100, v110, v111
	v_cvt_pk_bf16_f32 v101, v108, v109
	ds_bpermute_b32 v244, v253, v98
	ds_bpermute_b32 v245, v253, v99
	ds_bpermute_b32 v246, v253, v100
	ds_bpermute_b32 v247, v253, v101
	v_lshl_add_u64 v[238:239], v[112:113], 0, v[250:251]
	s_waitcnt lgkmcnt(4)
	global_store_dwordx4 v[236:237], v[240:243], off
	s_and_saveexec_b64 s[36:37], s[4:5]
	s_cbranch_execz .LBB0_1222
	v_lshlrev_b64 v[98:99], 6, v[182:183]
	v_lshl_add_u64 v[98:99], s[16:17], 0, v[98:99]
	v_lshl_add_u64 v[98:99], s[34:35], 2, v[98:99]
	s_lshl_b32 s8, s48, 2
	v_lshl_add_u64 v[98:99], v[98:99], 0, s[8:9]
	s_waitcnt lgkmcnt(4)
	v_add_f32_e32 v96, v96, v97
	global_store_dword v[98:99], v96, off
.LBB0_1222:
	s_or_b64 exec, exec, s[36:37]
	v_lshlrev_b32_e32 v96, 16, v140
	s_waitcnt lgkmcnt(0)
	v_and_b32_e32 v97, 0xffff0000, v140
	v_lshlrev_b32_e32 v98, 16, v141
	v_and_b32_e32 v99, 0xffff0000, v141
	v_lshlrev_b32_e32 v100, 16, v142
	v_and_b32_e32 v101, 0xffff0000, v142
	v_lshlrev_b32_e32 v102, 16, v143
	v_and_b32_e32 v103, 0xffff0000, v143
	v_pk_add_f32 v[94:95], v[94:95], v[98:99]
	v_pk_add_f32 v[92:93], v[92:93], v[96:97]
	v_pk_add_f32 v[96:97], v[90:91], v[102:103]
	v_pk_add_f32 v[90:91], v[88:89], v[100:101]
	v_mul_f32_e32 v88, v93, v93
	v_mul_f32_e32 v89, v95, v95
	v_fmac_f32_e32 v88, v92, v92
	v_fmac_f32_e32 v89, v94, v94
	v_add_f32_e32 v88, v88, v89
	v_mul_f32_e32 v89, v91, v91
	v_fmac_f32_e32 v89, v90, v90
	v_add_f32_e32 v88, v89, v88
	v_mul_f32_e32 v89, v97, v97
	v_fmac_f32_e32 v89, v96, v96
	v_add_f32_e32 v100, v89, v88
	v_cvt_pk_bf16_f32 v88, v92, v93
	v_cvt_pk_bf16_f32 v89, v94, v95
	v_lshlrev_b32_e32 v92, 16, v136
	v_and_b32_e32 v93, 0xffff0000, v136
	v_lshlrev_b32_e32 v94, 16, v137
	v_and_b32_e32 v95, 0xffff0000, v137
	v_cvt_pk_bf16_f32 v90, v90, v91
	v_cvt_pk_bf16_f32 v91, v96, v97
	v_lshlrev_b32_e32 v96, 16, v138
	v_and_b32_e32 v97, 0xffff0000, v138
	v_pk_add_f32 v[86:87], v[86:87], v[94:95]
	v_pk_add_f32 v[84:85], v[84:85], v[92:93]
	v_pk_add_f32 v[94:95], v[80:81], v[96:97]
	v_mul_f32_e32 v80, v85, v85
	v_mul_f32_e32 v81, v87, v87
	v_fmac_f32_e32 v80, v84, v84
	v_fmac_f32_e32 v81, v86, v86
	v_lshlrev_b32_e32 v98, 16, v139
	v_and_b32_e32 v99, 0xffff0000, v139
	v_add_f32_e32 v80, v80, v81
	v_mul_f32_e32 v81, v95, v95
	v_pk_add_f32 v[92:93], v[82:83], v[98:99]
	v_fmac_f32_e32 v81, v94, v94
	v_add_f32_e32 v80, v81, v80
	v_mul_f32_e32 v81, v93, v93
	v_fmac_f32_e32 v81, v92, v92
	v_add_f32_e32 v80, v81, v80
	v_add_f32_e32 v83, v100, v80
	ds_bpermute_b32 v98, v186, v83
	v_lshl_add_u64 v[80:81], s[14:15], 0, v[180:181]
	v_lshl_add_u64 v[96:97], v[168:169], 1, v[80:81]
	ds_bpermute_b32 v240, v253, v88
	ds_bpermute_b32 v241, v253, v89
	ds_bpermute_b32 v242, v253, v90
	ds_bpermute_b32 v243, v253, v91
	v_lshl_add_u64 v[236:237], v[96:97], 0, v[250:251]
	s_waitcnt lgkmcnt(4)
	global_store_dwordx4 v[238:239], v[244:247], off offset:256
	v_cvt_pk_bf16_f32 v82, v84, v85
	s_waitcnt lgkmcnt(4)
	v_add_f32_e32 v80, v83, v98
	ds_bpermute_b32 v81, v187, v80
	v_cvt_pk_bf16_f32 v83, v86, v87
	v_cvt_pk_bf16_f32 v84, v94, v95
	v_cvt_pk_bf16_f32 v85, v92, v93
	ds_bpermute_b32 v244, v253, v82
	ds_bpermute_b32 v245, v253, v83
	ds_bpermute_b32 v246, v253, v84
	ds_bpermute_b32 v247, v253, v85
	v_lshl_add_u64 v[238:239], v[96:97], 0, v[250:251]
	s_waitcnt lgkmcnt(4)
	global_store_dwordx4 v[236:237], v[240:243], off
	s_and_saveexec_b64 s[36:37], s[4:5]
	s_cbranch_execz .LBB0_1224
	v_lshlrev_b64 v[82:83], 6, v[178:179]
	v_lshl_add_u64 v[82:83], s[16:17], 0, v[82:83]
	v_lshl_add_u64 v[82:83], s[34:35], 2, v[82:83]
	s_lshl_b32 s8, s48, 2
	v_lshl_add_u64 v[82:83], v[82:83], 0, s[8:9]
	s_waitcnt lgkmcnt(4)
	v_add_f32_e32 v80, v80, v81
	global_store_dword v[82:83], v80, off
;     __device__ __forceinline__ void operator()(const f32x4 (&acc)[2][2][4][2], const Unit& u, int wr, int wc, int fr, int fq) const {
;     ...
;             u32x4 bw[4][2]; f32x4 bf[4][2][2];
; #pragma unroll
;             for (int m = 0; m < 4; ++m)
; #pragma unroll
;                 for (int bj = 0; bj < 2; ++bj) { const size_t off = (size_t)(row0 + ai * HALF + m * 16) * 1024 + col0 + bj * HALF;
;                     if (BASE_BF16) bw[m][bj] = *(const u32x4*)((const bf16_t*)base + off);
;                     else { bf[m][bj][0] = *(const f32x4*)((const float*)base + off); bf[m][bj][1] = *(const f32x4*)((const float*)base + off + 4); } }
;     ...
;             for (int m = 0; m < 4; ++m) {
;                 const int row = row0 + ai * HALF + m * 16; const size_t off = (size_t)row * 1024 + col0;
;                 float ss = 0.f;
; #pragma unroll
;                 for (int bj = 0; bj < 2; ++bj) {
;                     f32x4 b0, b1;
;                     if (BASE_BF16) { const u32x4 w = bw[m][bj];
;                         b0 = (f32x4){__builtin_bit_cast(float, w.x << 16), __builtin_bit_cast(float, w.x & 0xffff0000u), __builtin_bit_cast(float, w.y << 16), __builtin_bit_cast(float, w.y & 0xffff0000u)};
;                         b1 = (f32x4){__builtin_bit_cast(float, w.z << 16), __builtin_bit_cast(float, w.z & 0xffff0000u), __builtin_bit_cast(float, w.w << 16), __builtin_bit_cast(float, w.w & 0xffff0000u)}; }
;                     else { b0 = bf[m][bj][0]; b1 = bf[m][bj][1]; }
;                     const f32x4 v0 = acc[ai][bj][m][0] + b0, v1 = acc[ai][bj][m][1] + b1;
;                     ss += (v0[0] * v0[0] + v0[1] * v0[1]) + (v0[2] * v0[2] + v0[3] * v0[3]) + (v1[0] * v1[0] + v1[1] * v1[1]) + (v1[2] * v1[2] + v1[3] * v1[3]);
;                     if (OUT_BF16) { u32x4 w; w.x = cvt_pk_bf16(v0[0], v0[1]); w.y = cvt_pk_bf16(v0[2], v0[3]); w.z = cvt_pk_bf16(v1[0], v1[1]); w.w = cvt_pk_bf16(v1[2], v1[3]);
;                         *(u32x4*)((bf16_t*)out + off + bj * HALF) = w; }
;                     else { *(f32x4*)((float*)out + off + bj * HALF) = v0; *(f32x4*)((float*)out + off + bj * HALF + 4) = v1; }
;                 }
;                 ss += __shfl_xor(ss, 16); ss += __shfl_xor(ss, 32);
;                 if (fq == 0) sspart[(size_t)row * 16 + u.pn * 4 + wc] = ss;
.LBB0_1224:
	s_or_b64 exec, exec, s[36:37]
	v_lshlrev_b32_e32 v80, 16, v132
	s_waitcnt lgkmcnt(0)
	v_and_b32_e32 v81, 0xffff0000, v132
	v_lshlrev_b32_e32 v82, 16, v133
	v_and_b32_e32 v83, 0xffff0000, v133
	v_lshlrev_b32_e32 v84, 16, v134
	v_and_b32_e32 v85, 0xffff0000, v134
	v_lshlrev_b32_e32 v86, 16, v135
	v_and_b32_e32 v87, 0xffff0000, v135
	v_pk_add_f32 v[78:79], v[78:79], v[82:83]
	v_pk_add_f32 v[76:77], v[76:77], v[80:81]
	v_pk_add_f32 v[80:81], v[74:75], v[86:87]
	v_pk_add_f32 v[74:75], v[72:73], v[84:85]
	v_mul_f32_e32 v72, v77, v77
	v_mul_f32_e32 v73, v79, v79
	v_fmac_f32_e32 v72, v76, v76
	v_fmac_f32_e32 v73, v78, v78
	v_add_f32_e32 v72, v72, v73
	v_mul_f32_e32 v73, v75, v75
	v_fmac_f32_e32 v73, v74, v74
	v_add_f32_e32 v72, v73, v72
	v_mul_f32_e32 v73, v81, v81
	v_fmac_f32_e32 v73, v80, v80
	v_add_f32_e32 v84, v73, v72
	v_cvt_pk_bf16_f32 v72, v76, v77
	v_cvt_pk_bf16_f32 v73, v78, v79
	v_lshlrev_b32_e32 v76, 16, v128
	v_and_b32_e32 v77, 0xffff0000, v128
	v_lshlrev_b32_e32 v78, 16, v129
	v_and_b32_e32 v79, 0xffff0000, v129
	v_cvt_pk_bf16_f32 v74, v74, v75
	v_cvt_pk_bf16_f32 v75, v80, v81
	v_lshlrev_b32_e32 v80, 16, v130
	v_and_b32_e32 v81, 0xffff0000, v130
	v_pk_add_f32 v[70:71], v[70:71], v[78:79]
	v_pk_add_f32 v[68:69], v[68:69], v[76:77]
	v_pk_add_f32 v[78:79], v[64:65], v[80:81]
	v_mul_f32_e32 v64, v69, v69
	v_mul_f32_e32 v65, v71, v71
	v_fmac_f32_e32 v64, v68, v68
	v_fmac_f32_e32 v65, v70, v70
	v_lshlrev_b32_e32 v82, 16, v131
	v_and_b32_e32 v83, 0xffff0000, v131
	v_add_f32_e32 v64, v64, v65
	v_mul_f32_e32 v65, v79, v79
	v_pk_add_f32 v[76:77], v[66:67], v[82:83]
	v_fmac_f32_e32 v65, v78, v78
	v_add_f32_e32 v64, v65, v64
	v_mul_f32_e32 v65, v77, v77
	v_fmac_f32_e32 v65, v76, v76
	v_add_f32_e32 v64, v65, v64
	v_add_f32_e32 v67, v84, v64
	ds_bpermute_b32 v82, v186, v67
	v_lshl_add_u64 v[64:65], s[14:15], 0, v[176:177]
	v_lshl_add_u64 v[80:81], v[168:169], 1, v[64:65]
	ds_bpermute_b32 v240, v253, v72
	ds_bpermute_b32 v241, v253, v73
	ds_bpermute_b32 v242, v253, v74
	ds_bpermute_b32 v243, v253, v75
	v_lshl_add_u64 v[236:237], v[80:81], 0, v[250:251]
	s_waitcnt lgkmcnt(4)
	global_store_dwordx4 v[238:239], v[244:247], off offset:256
	v_cvt_pk_bf16_f32 v66, v68, v69
	s_waitcnt lgkmcnt(4)
	v_add_f32_e32 v64, v67, v82
	ds_bpermute_b32 v65, v187, v64
	v_cvt_pk_bf16_f32 v67, v70, v71
	v_cvt_pk_bf16_f32 v68, v78, v79
	v_cvt_pk_bf16_f32 v69, v76, v77
	ds_bpermute_b32 v244, v253, v66
	ds_bpermute_b32 v245, v253, v67
	ds_bpermute_b32 v246, v253, v68
	ds_bpermute_b32 v247, v253, v69
	v_lshl_add_u64 v[238:239], v[80:81], 0, v[250:251]
	s_waitcnt lgkmcnt(4)
	global_store_dwordx4 v[236:237], v[240:243], off
	s_and_saveexec_b64 s[36:37], s[4:5]
	s_cbranch_execz .LBB0_1226
	v_lshlrev_b64 v[66:67], 6, v[174:175]
	v_lshl_add_u64 v[66:67], s[16:17], 0, v[66:67]
	v_lshl_add_u64 v[66:67], s[34:35], 2, v[66:67]
	s_lshl_b32 s8, s48, 2
	v_lshl_add_u64 v[66:67], v[66:67], 0, s[8:9]
	s_waitcnt lgkmcnt(4)
	v_add_f32_e32 v64, v64, v65
	global_store_dword v[66:67], v64, off
.LBB0_1226:
	s_or_b64 exec, exec, s[36:37]
	v_add_u32_e32 v100, 0x80, v172
	v_ashrrev_i32_e32 v101, 31, v100
	v_lshlrev_b64 v[110:111], 11, v[100:101]
	s_waitcnt lgkmcnt(0)
	v_lshl_add_u64 v[64:65], v[170:171], 0, v[110:111]
	global_load_dwordx4 v[102:105], v[64:65], off
	global_load_dwordx4 v[106:109], v[64:65], off offset:256
	v_add_u32_e32 v96, 0x90, v172
	v_add_u32_e32 v92, 0xa0, v172
	v_add_u32_e32 v88, 0xb0, v172
	v_ashrrev_i32_e32 v97, 31, v96
	v_ashrrev_i32_e32 v93, 31, v92
	v_ashrrev_i32_e32 v89, 31, v88
	v_lshlrev_b64 v[98:99], 11, v[96:97]
	v_lshlrev_b64 v[94:95], 11, v[92:93]
	v_lshlrev_b64 v[90:91], 11, v[88:89]
	v_lshl_add_u64 v[64:65], v[170:171], 0, v[98:99]
	v_lshl_add_u64 v[66:67], v[170:171], 0, v[94:95]
	v_lshl_add_u64 v[112:113], v[170:171], 0, v[90:91]
	global_load_dwordx4 v[84:87], v[64:65], off
	global_load_dwordx4 v[80:83], v[64:65], off offset:256
	global_load_dwordx4 v[76:79], v[66:67], off
	global_load_dwordx4 v[72:75], v[66:67], off offset:256
	global_load_dwordx4 v[68:71], v[112:113], off
	s_nop 0
	global_load_dwordx4 v[64:67], v[112:113], off offset:256
	s_waitcnt vmcnt(7)
	v_lshlrev_b32_e32 v112, 16, v102
	v_and_b32_e32 v113, 0xffff0000, v102
	v_lshlrev_b32_e32 v102, 16, v103
	v_and_b32_e32 v103, 0xffff0000, v103
	v_lshlrev_b32_e32 v114, 16, v104
	v_and_b32_e32 v115, 0xffff0000, v104
	v_lshlrev_b32_e32 v104, 16, v105
	v_and_b32_e32 v105, 0xffff0000, v105
	s_waitcnt vmcnt(6)
	v_lshlrev_b32_e32 v116, 16, v106
	v_and_b32_e32 v117, 0xffff0000, v106
	v_lshlrev_b32_e32 v106, 16, v107
	v_and_b32_e32 v107, 0xffff0000, v107
	v_lshlrev_b32_e32 v118, 16, v108
	v_and_b32_e32 v119, 0xffff0000, v108
	v_lshlrev_b32_e32 v108, 16, v109
	v_and_b32_e32 v109, 0xffff0000, v109
	v_pk_add_f32 v[62:63], v[62:63], v[102:103]
	v_pk_add_f32 v[60:61], v[60:61], v[112:113]
	v_pk_add_f32 v[58:59], v[58:59], v[104:105]
	v_pk_add_f32 v[56:57], v[56:57], v[114:115]
	v_pk_add_f32 v[54:55], v[54:55], v[106:107]
	v_pk_add_f32 v[52:53], v[52:53], v[116:117]
	v_pk_add_f32 v[102:103], v[50:51], v[108:109]
	v_pk_add_f32 v[104:105], v[48:49], v[118:119]
	v_mul_f32_e32 v106, v61, v61
	v_mul_f32_e32 v107, v63, v63
	v_mul_f32_e32 v108, v57, v57
	v_mul_f32_e32 v109, v59, v59
	v_cvt_pk_bf16_f32 v48, v60, v61
	v_cvt_pk_bf16_f32 v49, v62, v63
	v_cvt_pk_bf16_f32 v50, v56, v57
	v_cvt_pk_bf16_f32 v51, v58, v59
	v_mul_f32_e32 v57, v53, v53
	v_mul_f32_e32 v59, v55, v55
	v_mul_f32_e32 v61, v105, v105
	v_fmac_f32_e32 v106, v60, v60
	v_fmac_f32_e32 v107, v62, v62
	v_fmac_f32_e32 v57, v52, v52
	v_fmac_f32_e32 v59, v54, v54
	v_mul_f32_e32 v63, v103, v103
	v_fmac_f32_e32 v108, v56, v56
	v_fmac_f32_e32 v61, v104, v104
	v_add_f32_e32 v56, v106, v107
	v_add_f32_e32 v57, v57, v59
	v_fmac_f32_e32 v109, v58, v58
	v_fmac_f32_e32 v63, v102, v102
	v_add_f32_e32 v56, v108, v56
	v_add_f32_e32 v57, v61, v57
	v_add_f32_e32 v56, v109, v56
	v_add_f32_e32 v57, v63, v57
	v_add_f32_e32 v58, v56, v57
	ds_bpermute_b32 v59, v186, v58
	v_lshl_add_u64 v[56:57], s[14:15], 0, v[110:111]
	v_lshl_add_u64 v[56:57], v[168:169], 1, v[56:57]
	ds_bpermute_b32 v240, v253, v48
	ds_bpermute_b32 v241, v253, v49
	ds_bpermute_b32 v242, v253, v50
	ds_bpermute_b32 v243, v253, v51
	v_lshl_add_u64 v[236:237], v[56:57], 0, v[250:251]
	s_waitcnt lgkmcnt(4)
	global_store_dwordx4 v[238:239], v[244:247], off offset:256
	s_waitcnt lgkmcnt(4)
	s_nop 0
	v_add_f32_e32 v48, v58, v59
	ds_bpermute_b32 v49, v187, v48
	v_cvt_pk_bf16_f32 v50, v52, v53
	v_cvt_pk_bf16_f32 v51, v54, v55
	v_cvt_pk_bf16_f32 v52, v104, v105
	v_cvt_pk_bf16_f32 v53, v102, v103
	ds_bpermute_b32 v244, v253, v50
	ds_bpermute_b32 v245, v253, v51
	ds_bpermute_b32 v246, v253, v52
	ds_bpermute_b32 v247, v253, v53
	v_lshl_add_u64 v[238:239], v[56:57], 0, v[250:251]
	s_waitcnt lgkmcnt(4)
	global_store_dwordx4 v[236:237], v[240:243], off
	s_and_saveexec_b64 s[36:37], s[4:5]
	s_cbranch_execz .LBB0_1228
; __device__ __forceinline__ unsigned cvt_pk_bf16(float lo, float hi) { unsigned r; asm volatile("v_cvt_pk_bf16_f32 %0, %1, %2" : "=v"(r) : "v"(lo), "v"(hi)); return r; }
;     __device__ __forceinline__ void operator()(const f32x4 (&acc)[2][2][4][2], const Unit& u, int wr, int wc, int fr, int fq) const {
;     ...
;             for (int m = 0; m < 4; ++m) {
;                 const int row = row0 + ai * HALF + m * 16; const size_t off = (size_t)row * 1024 + col0;
;                 float ss = 0.f;
; #pragma unroll
;                 for (int bj = 0; bj < 2; ++bj) {
;                     f32x4 b0, b1;
;                     if (BASE_BF16) { const u32x4 w = bw[m][bj];
;                         b0 = (f32x4){__builtin_bit_cast(float, w.x << 16), __builtin_bit_cast(float, w.x & 0xffff0000u), __builtin_bit_cast(float, w.y << 16), __builtin_bit_cast(float, w.y & 0xffff0000u)};
;                         b1 = (f32x4){__builtin_bit_cast(float, w.z << 16), __builtin_bit_cast(float, w.z & 0xffff0000u), __builtin_bit_cast(float, w.w << 16), __builtin_bit_cast(float, w.w & 0xffff0000u)}; }
;                     else { b0 = bf[m][bj][0]; b1 = bf[m][bj][1]; }
;                     const f32x4 v0 = acc[ai][bj][m][0] + b0, v1 = acc[ai][bj][m][1] + b1;
;                     ss += (v0[0] * v0[0] + v0[1] * v0[1]) + (v0[2] * v0[2] + v0[3] * v0[3]) + (v1[0] * v1[0] + v1[1] * v1[1]) + (v1[2] * v1[2] + v1[3] * v1[3]);
;                     if (OUT_BF16) { u32x4 w; w.x = cvt_pk_bf16(v0[0], v0[1]); w.y = cvt_pk_bf16(v0[2], v0[3]); w.z = cvt_pk_bf16(v1[0], v1[1]); w.w = cvt_pk_bf16(v1[2], v1[3]);
;                         *(u32x4*)((bf16_t*)out + off + bj * HALF) = w; }
;                     else { *(f32x4*)((float*)out + off + bj * HALF) = v0; *(f32x4*)((float*)out + off + bj * HALF + 4) = v1; }
;                 }
;                 ss += __shfl_xor(ss, 16); ss += __shfl_xor(ss, 32);
;                 if (fq == 0) sspart[(size_t)row * 16 + u.pn * 4 + wc] = ss;
	v_lshlrev_b64 v[50:51], 6, v[100:101]
	v_lshl_add_u64 v[50:51], s[16:17], 0, v[50:51]
	v_lshl_add_u64 v[50:51], s[34:35], 2, v[50:51]
	s_lshl_b32 s8, s48, 2
	v_lshl_add_u64 v[50:51], v[50:51], 0, s[8:9]
	s_waitcnt lgkmcnt(4)
	v_add_f32_e32 v48, v48, v49
	global_store_dword v[50:51], v48, off
.LBB0_1228:
	s_or_b64 exec, exec, s[36:37]
	s_waitcnt vmcnt(7)
	v_lshlrev_b32_e32 v48, 16, v84
	s_waitcnt lgkmcnt(0)
	v_and_b32_e32 v49, 0xffff0000, v84
	v_lshlrev_b32_e32 v50, 16, v85
	v_and_b32_e32 v51, 0xffff0000, v85
	v_lshlrev_b32_e32 v52, 16, v86
	v_and_b32_e32 v53, 0xffff0000, v86
	v_lshlrev_b32_e32 v54, 16, v87
	v_and_b32_e32 v55, 0xffff0000, v87
	v_pk_add_f32 v[46:47], v[46:47], v[50:51]
	v_pk_add_f32 v[44:45], v[44:45], v[48:49]
	v_pk_add_f32 v[48:49], v[42:43], v[54:55]
	v_pk_add_f32 v[42:43], v[40:41], v[52:53]
	v_mul_f32_e32 v40, v45, v45
	v_mul_f32_e32 v41, v47, v47
	v_fmac_f32_e32 v40, v44, v44
	v_fmac_f32_e32 v41, v46, v46
	v_add_f32_e32 v40, v40, v41
	v_mul_f32_e32 v41, v43, v43
	v_fmac_f32_e32 v41, v42, v42
	v_add_f32_e32 v40, v41, v40
	v_mul_f32_e32 v41, v49, v49
	v_fmac_f32_e32 v41, v48, v48
	v_add_f32_e32 v52, v41, v40
	v_cvt_pk_bf16_f32 v40, v44, v45
	v_cvt_pk_bf16_f32 v41, v46, v47
	s_waitcnt vmcnt(6)
	v_lshlrev_b32_e32 v44, 16, v80
	v_and_b32_e32 v45, 0xffff0000, v80
	v_lshlrev_b32_e32 v46, 16, v81
	v_and_b32_e32 v47, 0xffff0000, v81
	v_cvt_pk_bf16_f32 v42, v42, v43
	v_cvt_pk_bf16_f32 v43, v48, v49
	v_lshlrev_b32_e32 v48, 16, v82
	v_and_b32_e32 v49, 0xffff0000, v82
	v_pk_add_f32 v[38:39], v[38:39], v[46:47]
	v_pk_add_f32 v[36:37], v[36:37], v[44:45]
	v_pk_add_f32 v[46:47], v[32:33], v[48:49]
	v_mul_f32_e32 v32, v37, v37
	v_mul_f32_e32 v33, v39, v39
	v_fmac_f32_e32 v32, v36, v36
	v_fmac_f32_e32 v33, v38, v38
	v_lshlrev_b32_e32 v50, 16, v83
	v_and_b32_e32 v51, 0xffff0000, v83
	v_add_f32_e32 v32, v32, v33
	v_mul_f32_e32 v33, v47, v47
	v_pk_add_f32 v[44:45], v[34:35], v[50:51]
	v_fmac_f32_e32 v33, v46, v46
	v_add_f32_e32 v32, v33, v32
	v_mul_f32_e32 v33, v45, v45
	v_fmac_f32_e32 v33, v44, v44
	v_add_f32_e32 v32, v33, v32
	v_add_f32_e32 v35, v52, v32
	ds_bpermute_b32 v50, v186, v35
	v_lshl_add_u64 v[32:33], s[14:15], 0, v[98:99]
	v_lshl_add_u64 v[48:49], v[168:169], 1, v[32:33]
	ds_bpermute_b32 v240, v253, v40
	ds_bpermute_b32 v241, v253, v41
	ds_bpermute_b32 v242, v253, v42
	ds_bpermute_b32 v243, v253, v43
	v_lshl_add_u64 v[236:237], v[48:49], 0, v[250:251]
	s_waitcnt lgkmcnt(4)
	global_store_dwordx4 v[238:239], v[244:247], off offset:256
	v_cvt_pk_bf16_f32 v34, v36, v37
	s_waitcnt lgkmcnt(4)
	v_add_f32_e32 v32, v35, v50
	ds_bpermute_b32 v33, v187, v32
	v_cvt_pk_bf16_f32 v35, v38, v39
	v_cvt_pk_bf16_f32 v36, v46, v47
	v_cvt_pk_bf16_f32 v37, v44, v45
	ds_bpermute_b32 v244, v253, v34
	ds_bpermute_b32 v245, v253, v35
	ds_bpermute_b32 v246, v253, v36
	ds_bpermute_b32 v247, v253, v37
	v_lshl_add_u64 v[238:239], v[48:49], 0, v[250:251]
	s_waitcnt lgkmcnt(4)
	global_store_dwordx4 v[236:237], v[240:243], off
	s_and_saveexec_b64 s[36:37], s[4:5]
	s_cbranch_execz .LBB0_1230
	v_lshlrev_b64 v[34:35], 6, v[96:97]
	v_lshl_add_u64 v[34:35], s[16:17], 0, v[34:35]
	v_lshl_add_u64 v[34:35], s[34:35], 2, v[34:35]
	s_lshl_b32 s8, s48, 2
	v_lshl_add_u64 v[34:35], v[34:35], 0, s[8:9]
	s_waitcnt lgkmcnt(4)
	v_add_f32_e32 v32, v32, v33
	global_store_dword v[34:35], v32, off
; __device__ __forceinline__ unsigned cvt_pk_bf16(float lo, float hi) { unsigned r; asm volatile("v_cvt_pk_bf16_f32 %0, %1, %2" : "=v"(r) : "v"(lo), "v"(hi)); return r; }
;     __device__ __forceinline__ void operator()(const f32x4 (&acc)[2][2][4][2], const Unit& u, int wr, int wc, int fr, int fq) const {
;     ...
;             for (int m = 0; m < 4; ++m) {
;                 const int row = row0 + ai * HALF + m * 16; const size_t off = (size_t)row * 1024 + col0;
;                 float ss = 0.f;
; #pragma unroll
;                 for (int bj = 0; bj < 2; ++bj) {
;                     f32x4 b0, b1;
;                     if (BASE_BF16) { const u32x4 w = bw[m][bj];
;                         b0 = (f32x4){__builtin_bit_cast(float, w.x << 16), __builtin_bit_cast(float, w.x & 0xffff0000u), __builtin_bit_cast(float, w.y << 16), __builtin_bit_cast(float, w.y & 0xffff0000u)};
;                         b1 = (f32x4){__builtin_bit_cast(float, w.z << 16), __builtin_bit_cast(float, w.z & 0xffff0000u), __builtin_bit_cast(float, w.w << 16), __builtin_bit_cast(float, w.w & 0xffff0000u)}; }
;                     else { b0 = bf[m][bj][0]; b1 = bf[m][bj][1]; }
;                     const f32x4 v0 = acc[ai][bj][m][0] + b0, v1 = acc[ai][bj][m][1] + b1;
;                     ss += (v0[0] * v0[0] + v0[1] * v0[1]) + (v0[2] * v0[2] + v0[3] * v0[3]) + (v1[0] * v1[0] + v1[1] * v1[1]) + (v1[2] * v1[2] + v1[3] * v1[3]);
;                     if (OUT_BF16) { u32x4 w; w.x = cvt_pk_bf16(v0[0], v0[1]); w.y = cvt_pk_bf16(v0[2], v0[3]); w.z = cvt_pk_bf16(v1[0], v1[1]); w.w = cvt_pk_bf16(v1[2], v1[3]);
;                         *(u32x4*)((bf16_t*)out + off + bj * HALF) = w; }
;                     else { *(f32x4*)((float*)out + off + bj * HALF) = v0; *(f32x4*)((float*)out + off + bj * HALF + 4) = v1; }
;                 }
;                 ss += __shfl_xor(ss, 16); ss += __shfl_xor(ss, 32);
;                 if (fq == 0) sspart[(size_t)row * 16 + u.pn * 4 + wc] = ss;
;             }
.LBB0_1230:
	s_or_b64 exec, exec, s[36:37]
	s_waitcnt vmcnt(7)
	v_lshlrev_b32_e32 v32, 16, v76
	s_waitcnt lgkmcnt(0)
	v_and_b32_e32 v33, 0xffff0000, v76
	v_lshlrev_b32_e32 v34, 16, v77
	v_and_b32_e32 v35, 0xffff0000, v77
	v_lshlrev_b32_e32 v36, 16, v78
	v_and_b32_e32 v37, 0xffff0000, v78
	v_lshlrev_b32_e32 v38, 16, v79
	v_and_b32_e32 v39, 0xffff0000, v79
	v_pk_add_f32 v[30:31], v[30:31], v[34:35]
	v_pk_add_f32 v[28:29], v[28:29], v[32:33]
	v_pk_add_f32 v[32:33], v[26:27], v[38:39]
	v_pk_add_f32 v[26:27], v[24:25], v[36:37]
	v_mul_f32_e32 v24, v29, v29
	v_mul_f32_e32 v25, v31, v31
	v_fmac_f32_e32 v24, v28, v28
	v_fmac_f32_e32 v25, v30, v30
	v_add_f32_e32 v24, v24, v25
	v_mul_f32_e32 v25, v27, v27
	v_fmac_f32_e32 v25, v26, v26
	v_add_f32_e32 v24, v25, v24
	v_mul_f32_e32 v25, v33, v33
	v_fmac_f32_e32 v25, v32, v32
	v_add_f32_e32 v36, v25, v24
	v_cvt_pk_bf16_f32 v24, v28, v29
	v_cvt_pk_bf16_f32 v25, v30, v31
	s_waitcnt vmcnt(6)
	v_lshlrev_b32_e32 v28, 16, v72
	v_and_b32_e32 v29, 0xffff0000, v72
	v_lshlrev_b32_e32 v30, 16, v73
	v_and_b32_e32 v31, 0xffff0000, v73
	v_cvt_pk_bf16_f32 v26, v26, v27
	v_cvt_pk_bf16_f32 v27, v32, v33
	v_lshlrev_b32_e32 v32, 16, v74
	v_and_b32_e32 v33, 0xffff0000, v74
	v_pk_add_f32 v[22:23], v[22:23], v[30:31]
	v_pk_add_f32 v[20:21], v[20:21], v[28:29]
	v_pk_add_f32 v[30:31], v[16:17], v[32:33]
	v_mul_f32_e32 v16, v21, v21
	v_mul_f32_e32 v17, v23, v23
	v_fmac_f32_e32 v16, v20, v20
	v_fmac_f32_e32 v17, v22, v22
	v_lshlrev_b32_e32 v34, 16, v75
	v_and_b32_e32 v35, 0xffff0000, v75
	v_add_f32_e32 v16, v16, v17
	v_mul_f32_e32 v17, v31, v31
	v_pk_add_f32 v[28:29], v[18:19], v[34:35]
	v_fmac_f32_e32 v17, v30, v30
	v_add_f32_e32 v16, v17, v16
	v_mul_f32_e32 v17, v29, v29
	v_fmac_f32_e32 v17, v28, v28
	v_add_f32_e32 v16, v17, v16
	v_add_f32_e32 v19, v36, v16
	ds_bpermute_b32 v34, v186, v19
	v_lshl_add_u64 v[16:17], s[14:15], 0, v[94:95]
	v_lshl_add_u64 v[32:33], v[168:169], 1, v[16:17]
	ds_bpermute_b32 v240, v253, v24
	ds_bpermute_b32 v241, v253, v25
	ds_bpermute_b32 v242, v253, v26
	ds_bpermute_b32 v243, v253, v27
	v_lshl_add_u64 v[236:237], v[32:33], 0, v[250:251]
	s_waitcnt lgkmcnt(4)
	global_store_dwordx4 v[238:239], v[244:247], off offset:256
	v_cvt_pk_bf16_f32 v18, v20, v21
	s_waitcnt lgkmcnt(4)
	v_add_f32_e32 v16, v19, v34
	ds_bpermute_b32 v17, v187, v16
	v_cvt_pk_bf16_f32 v19, v22, v23
	v_cvt_pk_bf16_f32 v20, v30, v31
	v_cvt_pk_bf16_f32 v21, v28, v29
	ds_bpermute_b32 v244, v253, v18
	ds_bpermute_b32 v245, v253, v19
	ds_bpermute_b32 v246, v253, v20
	ds_bpermute_b32 v247, v253, v21
	v_lshl_add_u64 v[238:239], v[32:33], 0, v[250:251]
	s_waitcnt lgkmcnt(4)
	global_store_dwordx4 v[236:237], v[240:243], off
	s_and_saveexec_b64 s[36:37], s[4:5]
	s_cbranch_execz .LBB0_1232
	v_lshlrev_b64 v[18:19], 6, v[92:93]
	v_lshl_add_u64 v[18:19], s[16:17], 0, v[18:19]
	v_lshl_add_u64 v[18:19], s[34:35], 2, v[18:19]
	s_lshl_b32 s8, s48, 2
	v_lshl_add_u64 v[18:19], v[18:19], 0, s[8:9]
	s_waitcnt lgkmcnt(4)
	v_add_f32_e32 v16, v16, v17
	global_store_dword v[18:19], v16, off
.LBB0_1232:
	s_or_b64 exec, exec, s[36:37]
	s_waitcnt vmcnt(7)
	v_lshlrev_b32_e32 v16, 16, v68
	s_waitcnt lgkmcnt(0)
	v_and_b32_e32 v17, 0xffff0000, v68
	v_lshlrev_b32_e32 v18, 16, v69
	v_and_b32_e32 v19, 0xffff0000, v69
	v_lshlrev_b32_e32 v20, 16, v70
	v_and_b32_e32 v21, 0xffff0000, v70
	v_lshlrev_b32_e32 v22, 16, v71
	v_and_b32_e32 v23, 0xffff0000, v71
	v_pk_add_f32 v[14:15], v[14:15], v[18:19]
	v_pk_add_f32 v[12:13], v[12:13], v[16:17]
	v_pk_add_f32 v[16:17], v[10:11], v[22:23]
	v_pk_add_f32 v[10:11], v[8:9], v[20:21]
	v_mul_f32_e32 v8, v13, v13
	v_mul_f32_e32 v9, v15, v15
	v_fmac_f32_e32 v8, v12, v12
	v_fmac_f32_e32 v9, v14, v14
	v_add_f32_e32 v8, v8, v9
	v_mul_f32_e32 v9, v11, v11
	v_fmac_f32_e32 v9, v10, v10
	v_add_f32_e32 v8, v9, v8
	v_mul_f32_e32 v9, v17, v17
	v_fmac_f32_e32 v9, v16, v16
	v_add_f32_e32 v20, v9, v8
	v_cvt_pk_bf16_f32 v8, v12, v13
	v_cvt_pk_bf16_f32 v9, v14, v15
	s_waitcnt vmcnt(6)
	v_lshlrev_b32_e32 v12, 16, v64
	v_and_b32_e32 v13, 0xffff0000, v64
	v_lshlrev_b32_e32 v14, 16, v65
	v_and_b32_e32 v15, 0xffff0000, v65
	v_cvt_pk_bf16_f32 v10, v10, v11
	v_cvt_pk_bf16_f32 v11, v16, v17
	v_lshlrev_b32_e32 v16, 16, v66
	v_and_b32_e32 v17, 0xffff0000, v66
	v_pk_add_f32 v[6:7], v[6:7], v[14:15]
	v_pk_add_f32 v[4:5], v[4:5], v[12:13]
	v_pk_add_f32 v[14:15], v[0:1], v[16:17]
	v_mul_f32_e32 v0, v5, v5
	v_mul_f32_e32 v1, v7, v7
	v_fmac_f32_e32 v0, v4, v4
	v_fmac_f32_e32 v1, v6, v6
	v_lshlrev_b32_e32 v18, 16, v67
	v_and_b32_e32 v19, 0xffff0000, v67
	v_add_f32_e32 v0, v0, v1
	v_mul_f32_e32 v1, v15, v15
	v_pk_add_f32 v[12:13], v[2:3], v[18:19]
	v_fmac_f32_e32 v1, v14, v14
	v_add_f32_e32 v0, v1, v0
	v_mul_f32_e32 v1, v13, v13
	v_fmac_f32_e32 v1, v12, v12
	v_add_f32_e32 v0, v1, v0
	v_add_f32_e32 v3, v20, v0
	ds_bpermute_b32 v18, v186, v3
	v_lshl_add_u64 v[0:1], s[14:15], 0, v[90:91]
	v_lshl_add_u64 v[16:17], v[168:169], 1, v[0:1]
	ds_bpermute_b32 v240, v253, v8
	ds_bpermute_b32 v241, v253, v9
	ds_bpermute_b32 v242, v253, v10
	ds_bpermute_b32 v243, v253, v11
	v_lshl_add_u64 v[236:237], v[16:17], 0, v[250:251]
	s_waitcnt lgkmcnt(4)
	global_store_dwordx4 v[238:239], v[244:247], off offset:256
	v_cvt_pk_bf16_f32 v2, v4, v5
	s_waitcnt lgkmcnt(4)
	v_add_f32_e32 v0, v3, v18
	ds_bpermute_b32 v1, v187, v0
	v_cvt_pk_bf16_f32 v3, v6, v7
	v_cvt_pk_bf16_f32 v4, v14, v15
	v_cvt_pk_bf16_f32 v5, v12, v13
	ds_bpermute_b32 v244, v253, v2
	ds_bpermute_b32 v245, v253, v3
	ds_bpermute_b32 v246, v253, v4
	ds_bpermute_b32 v247, v253, v5
	v_lshl_add_u64 v[238:239], v[16:17], 0, v[250:251]
	s_waitcnt lgkmcnt(4)
	global_store_dwordx4 v[236:237], v[240:243], off
	s_waitcnt lgkmcnt(0)
	global_store_dwordx4 v[238:239], v[244:247], off offset:256
	s_and_saveexec_b64 s[36:37], s[4:5]
	s_cbranch_execz .LBB0_1234
	v_lshlrev_b64 v[2:3], 6, v[88:89]
	v_lshl_add_u64 v[2:3], s[16:17], 0, v[2:3]
	v_lshl_add_u64 v[2:3], s[34:35], 2, v[2:3]
	s_lshl_b32 s8, s48, 2
	v_lshl_add_u64 v[2:3], v[2:3], 0, s[8:9]
	s_waitcnt lgkmcnt(0)
	v_add_f32_e32 v0, v0, v1
	global_store_dword v[2:3], v0, off
